# w_o residual epilogue: x loads / y stores re-laid out with permlane16/32 swaps so each wave instruction touches full 64B row segments (coalesced) instead of strided 16B pieces
# speedup vs baseline: 1.0083x; 1.0083x over previous
;     DI void operator()(AccRef acc, const Unit& u, int wr, int wc, int fr, int fq) const {
;     ...
; #pragma unroll
;         for (int ai = 0; ai < 2; ++ai) {
;             const int rb = u.pm * 256 + ai * 128 + wr * 64 + fr;
;             int mb, pos0, kv0; row_info(rb, mb, pos0, kv0);
;             f32x4 gt[2][2], gs[2][2];
; #pragma unroll
;             for (int bj = 0; bj < 2; ++bj)
; #pragma unroll
;                 for (int n = 0; n < 2; ++n) {
;                     const int c = u.pn * 256 + bj * 128 + cl + 4 * n;
;                     gt[bj][n] = *(const f32x4*)(gate + (size_t)mb * 6144 + c);
;                     if (ap) { const f32x4 g = *(const f32x4*)(gn + c), s = *(const f32x4*)(scn + (size_t)mb * 6144 + c); gs[bj][n] = g * (s + 1.f); }
;                 }
; #pragma unroll
;             for (int m = 0; m < 4; ++m) {
;                 const int row = rb + 16 * m;
;                 const float* xi = row < MP ? xin_p + (size_t)row * 1024 : xin_s + (size_t)(row - MP) * 1024;
;                 float s = 0.f;
; #pragma unroll
;                 for (int bj = 0; bj < 2; ++bj) {
;                     const int c = u.pn * 256 + bj * 128 + cl;
;                     float v[8];
; #pragma unroll
;                     for (int n = 0; n < 2; ++n) {
;                         const f32x4 x = *(const f32x4*)(xi + c + 4 * n);
;                         const f32x4 y = x + gt[bj][n] * acc[ai][bj][m][n];
;                         *(f32x4*)(xout + (size_t)row * 1024 + c + 4 * n) = y;
.LBB0_1094:
	v_readlane_b32 s3, v253, 32
	v_mbcnt_lo_u32_b32 v100, -1, 0
	v_mbcnt_hi_u32_b32 v100, -1, v100
	s_mov_b32 s3, s30
	v_and_b32_e32 v202, 15, v100
	v_bfe_u32 v204, v100, 4, 2
	s_mov_b32 s12, s36
	s_lshl_b32 s16, s16, 8
	s_lshl_b32 s3, s3, 6
	s_add_i32 s3, s3, s16
	v_add_u32_e32 v192, s3, v202
	s_lshl_b32 s13, s12, 5
	s_lshl_b32 s3, s2, 8
	v_add_u32_e32 v224, 0xffffc000, v192
	s_add_i32 s13, s13, s3
	v_lshrrev_b32_e32 v101, 6, v224
	v_lshl_add_u32 v188, v204, 3, s13
	v_ashrrev_i32_e32 v100, 11, v192
	v_add_u32_e32 v101, 8, v101
	v_cmp_gt_i32_e32 vcc, s94, v192
	v_mov_b64_e32 v[102:103], s[60:61]
	v_ashrrev_i32_e32 v189, 31, v188
	v_cndmask_b32_e32 v104, v101, v100, vcc
	v_mov_b64_e32 v[100:101], s[8:9]
	v_mad_i64_i32 v[100:101], s[16:17], v104, s75, v[100:101]
	v_mad_i64_i32 v[102:103], s[16:17], v104, s75, v[102:103]
	v_lshlrev_b64 v[190:191], 2, v[188:189]
	v_lshl_add_u64 v[104:105], v[100:101], 0, v[190:191]
	v_lshl_add_u64 v[194:195], s[72:73], 0, v[190:191]
	v_lshl_add_u64 v[168:169], v[102:103], 0, v[190:191]
	global_load_dwordx4 v[108:111], v[104:105], off offset:16
	global_load_dwordx4 v[116:119], v[104:105], off
	global_load_dwordx4 v[148:151], v[194:195], off offset:16
	global_load_dwordx4 v[164:167], v[194:195], off
	global_load_dwordx4 v[160:163], v[168:169], off offset:16
	global_load_dwordx4 v[172:175], v[168:169], off
	global_load_dwordx4 v[100:103], v[104:105], off offset:528
	s_nop 0
	global_load_dwordx4 v[104:107], v[104:105], off offset:512
	s_nop 0
	global_load_dwordx4 v[144:147], v[194:195], off offset:528
	global_load_dwordx4 v[156:159], v[194:195], off offset:512
	global_load_dwordx4 v[152:155], v[168:169], off offset:528
	s_nop 0
	global_load_dwordx4 v[168:171], v[168:169], off offset:512
	s_movk_i32 s3, 0x3fff
	v_cmp_lt_i32_e32 vcc, s3, v192
	s_and_saveexec_b64 s[16:17], vcc
	s_xor_b64 s[16:17], exec, s[16:17]
	v_lshlrev_b64 v[196:197], 12, v[224:225]
	v_mov_b32_e32 v193, v225
	v_lshl_add_u64 v[198:199], s[20:21], 0, v[196:197]
	v_lshlrev_b64 v[196:197], 12, v[192:193]
	s_andn2_saveexec_b64 s[16:17], s[16:17]
	v_ashrrev_i32_e32 v193, 31, v192
	v_lshlrev_b64 v[196:197], 12, v[192:193]
	v_lshl_add_u64 v[198:199], s[42:43], 0, v[196:197]
	s_or_b64 exec, exec, s[16:17]
	s_sub_u32 s82, s20, 0x4000000
	s_subb_u32 s83, s21, 0
	s_cmp_ge_u32 s16, 0x4000
	s_cselect_b32 s82, s82, s42
	s_cselect_b32 s83, s83, s43
	v_lshl_add_u32 v206, v192, 12, v190
	v_lshlrev_b32_e32 v213, 4, v204
	v_sub_u32_e32 v206, v206, v213
	v_lshlrev_b32_e32 v213, 11, v192
	v_lshlrev_b32_e32 v209, 6, v192
	v_mov_b32_e32 v207, v206
	v_lshl_add_u32 v208, v188, 1, v213
	global_load_dwordx4 v[232:235], v206, s[82:83] offset:64
	global_load_dwordx4 v[240:243], v206, s[82:83] offset:576
	global_load_dwordx4 v[228:231], v206, s[82:83]
	global_load_dwordx4 v[236:239], v206, s[82:83] offset:512
	v_add_u32_e32 v206, 0x10000, v206
	global_load_dwordx4 v[248:251], v206, s[82:83] offset:64
	global_load_dwordx4 v[220:223], v206, s[82:83] offset:576
	global_load_dwordx4 v[244:247], v206, s[82:83]
	global_load_dwordx4 v[216:219], v206, s[82:83] offset:512
	v_add_u32_e32 v206, 0x10000, v206
	s_waitcnt vmcnt(8)
	v_pk_add_f32 v[172:173], v[172:173], 1.0 op_sel_hi:[1,0]
	v_pk_add_f32 v[154:155], v[154:155], 1.0 op_sel_hi:[1,0]
	v_pk_mul_f32 v[164:165], v[164:165], v[172:173]
	v_pk_add_f32 v[172:173], v[160:161], 1.0 op_sel_hi:[1,0]
	v_pk_add_f32 v[160:161], v[162:163], 1.0 op_sel_hi:[1,0]
	v_pk_mul_f32 v[162:163], v[148:149], v[172:173]
	v_pk_mul_f32 v[160:161], v[150:151], v[160:161]
	v_pk_add_f32 v[148:149], v[170:171], 1.0 op_sel_hi:[1,0]
	v_pk_add_f32 v[150:151], v[168:169], 1.0 op_sel_hi:[1,0]
	v_pk_mul_f32 v[146:147], v[146:147], v[154:155]
	v_lshl_add_u64 v[154:155], v[198:199], 0, v[190:191]
	v_pk_mul_f32 v[148:149], v[158:159], v[148:149]
	v_pk_mul_f32 v[150:151], v[156:157], v[150:151]
	v_pk_add_f32 v[174:175], v[174:175], 1.0 op_sel_hi:[1,0]
	v_pk_add_f32 v[152:153], v[152:153], 1.0 op_sel_hi:[1,0]
	v_pk_mul_f32 v[166:167], v[166:167], v[174:175]
	v_pk_mul_f32 v[144:145], v[144:145], v[152:153]
	v_lshlrev_b64 v[152:153], 11, v[192:193]
	v_lshl_add_u64 v[152:153], s[64:65], 0, v[152:153]
	v_lshlrev_b32_e32 v202, 2, v202
	v_lshl_add_u32 v202, v204, 6, v202
	v_xor_b32_e32 v203, 64, v202
	s_lshl_b32 s2, s2, 2
	v_xor_b32_e32 v202, 0x80, v202
	s_ashr_i32 s3, s2, 31
	s_ashr_i32 s13, s12, 31
	s_lshl_b64 s[2:3], s[2:3], 2
	s_add_u32 s16, s39, s2
	s_addc_u32 s17, s40, s3
	s_lshl_b64 s[2:3], s[12:13], 2
	s_add_u32 s90, s16, s2
	v_cmp_eq_u32_e32 vcc, 0, v204
	s_addc_u32 s91, s17, s3
	s_waitcnt vmcnt(4)
; DI u32x4 pack8(const float* v) { u32x4 w; w.x = pk2(v[0], v[1]); w.y = pk2(v[2], v[3]); w.z = pk2(v[4], v[5]); w.w = pk2(v[6], v[7]); return w; }
; #define xor16_32(s) xor16_32_l((s), fr + 16 * fq)
;     DI void operator()(AccRef acc, const Unit& u, int wr, int wc, int fr, int fq) const {
;     ...
;             for (int m = 0; m < 4; ++m) {
;                 const int row = rb + 16 * m;
;                 const float* xi = row < MP ? xin_p + (size_t)row * 1024 : xin_s + (size_t)(row - MP) * 1024;
;                 float s = 0.f;
; #pragma unroll
;                 for (int bj = 0; bj < 2; ++bj) {
;                     const int c = u.pn * 256 + bj * 128 + cl;
;                     float v[8];
; #pragma unroll
;                     for (int n = 0; n < 2; ++n) {
;                         const f32x4 x = *(const f32x4*)(xi + c + 4 * n);
;                         const f32x4 y = x + gt[bj][n] * acc[ai][bj][m][n];
;                         *(f32x4*)(xout + (size_t)row * 1024 + c + 4 * n) = y;
; #pragma unroll
;                         for (int j = 0; j < 4; ++j) { s += y[j] * y[j]; v[4 * n + j] = ap ? y[j] * gs[bj][n][j] : 0.f; }
;                     }
;                     if (ap) *(u32x4*)(ap + (size_t)row * 1024 + c) = pack8(v);
;                 }
;                 s = xor16_32(s);
;                 if (fq == 0) ssq[(size_t)row * 16 + u.pn * 4 + wc] = s;
	v_permlane32_swap_b32_e32 v228, v232
	v_permlane32_swap_b32_e32 v229, v233
	v_permlane32_swap_b32_e32 v230, v234
	v_permlane32_swap_b32_e32 v231, v235
	v_permlane32_swap_b32_e32 v236, v240
	v_permlane32_swap_b32_e32 v237, v241
	v_permlane32_swap_b32_e32 v238, v242
	v_permlane32_swap_b32_e32 v239, v243
	v_permlane16_swap_b32_e32 v228, v232
	v_permlane16_swap_b32_e32 v229, v233
	v_permlane16_swap_b32_e32 v230, v234
	v_permlane16_swap_b32_e32 v231, v235
	v_permlane16_swap_b32_e32 v236, v240
	v_permlane16_swap_b32_e32 v237, v241
	v_permlane16_swap_b32_e32 v238, v242
	v_permlane16_swap_b32_e32 v239, v243
	v_pk_fma_f32 v[140:141], v[140:141], v[116:117], v[228:229]
	v_pk_fma_f32 v[142:143], v[142:143], v[118:119], v[230:231]
	v_mul_f32_e32 v210, v141, v141
	v_fmac_f32_e32 v210, v140, v140
	v_fmac_f32_e32 v210, v142, v142
	v_fmac_f32_e32 v210, v143, v143
	v_pk_mul_f32 v[228:229], v[164:165], v[140:141]
	v_pk_mul_f32 v[230:231], v[166:167], v[142:143]
	v_pk_fma_f32 v[136:137], v[136:137], v[108:109], v[232:233]
	v_pk_fma_f32 v[138:139], v[138:139], v[110:111], v[234:235]
	v_fmac_f32_e32 v210, v136, v136
	v_fmac_f32_e32 v210, v137, v137
	v_fmac_f32_e32 v210, v138, v138
	v_fmac_f32_e32 v210, v139, v139
	v_pk_mul_f32 v[232:233], v[162:163], v[136:137]
	v_pk_mul_f32 v[234:235], v[160:161], v[138:139]
	v_cvt_pk_bf16_f32 v228, v228, v229
	v_cvt_pk_bf16_f32 v229, v230, v231
	v_cvt_pk_bf16_f32 v230, v232, v233
	v_cvt_pk_bf16_f32 v231, v234, v235
	global_store_dwordx4 v208, v[228:231], s[64:65]
	v_pk_fma_f32 v[132:133], v[132:133], v[104:105], v[236:237]
	v_pk_fma_f32 v[134:135], v[134:135], v[106:107], v[238:239]
	v_fmac_f32_e32 v210, v132, v132
	v_fmac_f32_e32 v210, v133, v133
	v_fmac_f32_e32 v210, v134, v134
	v_fmac_f32_e32 v210, v135, v135
	v_pk_mul_f32 v[236:237], v[150:151], v[132:133]
	v_pk_mul_f32 v[238:239], v[148:149], v[134:135]
	v_pk_fma_f32 v[128:129], v[128:129], v[100:101], v[240:241]
	v_pk_fma_f32 v[130:131], v[130:131], v[102:103], v[242:243]
	v_fmac_f32_e32 v210, v128, v128
	v_fmac_f32_e32 v210, v129, v129
	v_fmac_f32_e32 v210, v130, v130
	v_fmac_f32_e32 v210, v131, v131
	v_pk_mul_f32 v[240:241], v[144:145], v[128:129]
	v_pk_mul_f32 v[242:243], v[146:147], v[130:131]
	v_cvt_pk_bf16_f32 v236, v236, v237
	v_cvt_pk_bf16_f32 v237, v238, v239
	v_cvt_pk_bf16_f32 v238, v240, v241
	v_cvt_pk_bf16_f32 v239, v242, v243
	global_store_dwordx4 v208, v[236:239], s[64:65] offset:256
	ds_bpermute_b32 v211, v203, v210
	v_permlane16_swap_b32_e32 v140, v136
	v_permlane16_swap_b32_e32 v141, v137
	v_permlane16_swap_b32_e32 v142, v138
	v_permlane16_swap_b32_e32 v143, v139
	v_permlane16_swap_b32_e32 v132, v128
	v_permlane16_swap_b32_e32 v133, v129
	v_permlane16_swap_b32_e32 v134, v130
	v_permlane16_swap_b32_e32 v135, v131
	v_permlane32_swap_b32_e32 v140, v136
	v_permlane32_swap_b32_e32 v141, v137
	v_permlane32_swap_b32_e32 v142, v138
	v_permlane32_swap_b32_e32 v143, v139
	v_permlane32_swap_b32_e32 v132, v128
	v_permlane32_swap_b32_e32 v133, v129
	v_permlane32_swap_b32_e32 v134, v130
	v_permlane32_swap_b32_e32 v135, v131
	global_store_dwordx4 v207, v[140:143], s[92:93]
	global_store_dwordx4 v207, v[136:139], s[92:93] offset:64
	global_store_dwordx4 v207, v[132:135], s[92:93] offset:512
	global_store_dwordx4 v207, v[128:131], s[92:93] offset:576
	v_add_u32_e32 v207, 0x10000, v207
	global_load_dwordx4 v[232:235], v206, s[82:83] offset:64
	global_load_dwordx4 v[240:243], v206, s[82:83] offset:576
	global_load_dwordx4 v[228:231], v206, s[82:83]
	global_load_dwordx4 v[236:239], v206, s[82:83] offset:512
	s_waitcnt lgkmcnt(0)
	v_add_f32_e32 v211, v210, v211
	ds_bpermute_b32 v212, v202, v211
	v_add_u32_e32 v208, 0x8000, v208
	s_waitcnt lgkmcnt(0)
	v_add_f32_e32 v211, v211, v212
	s_mov_b64 exec, 0xffff
	global_store_dword v209, v211, s[90:91]
	s_mov_b64 exec, -1
	v_add_u32_e32 v209, 0x400, v209
	s_waitcnt vmcnt(11)
	v_permlane32_swap_b32_e32 v244, v248
	v_permlane32_swap_b32_e32 v245, v249
	v_permlane32_swap_b32_e32 v246, v250
	v_permlane32_swap_b32_e32 v247, v251
	v_permlane32_swap_b32_e32 v216, v220
	v_permlane32_swap_b32_e32 v217, v221
	v_permlane32_swap_b32_e32 v218, v222
	v_permlane32_swap_b32_e32 v219, v223
	v_permlane16_swap_b32_e32 v244, v248
	v_permlane16_swap_b32_e32 v245, v249
	v_permlane16_swap_b32_e32 v246, v250
	v_permlane16_swap_b32_e32 v247, v251
	v_permlane16_swap_b32_e32 v216, v220
	v_permlane16_swap_b32_e32 v217, v221
	v_permlane16_swap_b32_e32 v218, v222
	v_permlane16_swap_b32_e32 v219, v223
	v_pk_fma_f32 v[124:125], v[124:125], v[116:117], v[244:245]
	v_pk_fma_f32 v[126:127], v[126:127], v[118:119], v[246:247]
	v_mul_f32_e32 v210, v125, v125
	v_fmac_f32_e32 v210, v124, v124
	v_fmac_f32_e32 v210, v126, v126
	v_fmac_f32_e32 v210, v127, v127
	v_pk_mul_f32 v[244:245], v[164:165], v[124:125]
	v_pk_mul_f32 v[246:247], v[166:167], v[126:127]
	v_pk_fma_f32 v[120:121], v[120:121], v[108:109], v[248:249]
	v_pk_fma_f32 v[122:123], v[122:123], v[110:111], v[250:251]
	v_fmac_f32_e32 v210, v120, v120
	v_fmac_f32_e32 v210, v121, v121
	v_fmac_f32_e32 v210, v122, v122
	v_fmac_f32_e32 v210, v123, v123
	v_pk_mul_f32 v[248:249], v[162:163], v[120:121]
	v_pk_mul_f32 v[250:251], v[160:161], v[122:123]
	v_cvt_pk_bf16_f32 v244, v244, v245
	v_cvt_pk_bf16_f32 v245, v246, v247
	v_cvt_pk_bf16_f32 v246, v248, v249
	v_cvt_pk_bf16_f32 v247, v250, v251
	global_store_dwordx4 v208, v[244:247], s[64:65]
	v_pk_fma_f32 v[112:113], v[112:113], v[104:105], v[216:217]
	v_pk_fma_f32 v[114:115], v[114:115], v[106:107], v[218:219]
	v_fmac_f32_e32 v210, v112, v112
	v_fmac_f32_e32 v210, v113, v113
	v_fmac_f32_e32 v210, v114, v114
	v_fmac_f32_e32 v210, v115, v115
	v_pk_mul_f32 v[216:217], v[150:151], v[112:113]
; DI u32x4 pack8(const float* v) { u32x4 w; w.x = pk2(v[0], v[1]); w.y = pk2(v[2], v[3]); w.z = pk2(v[4], v[5]); w.w = pk2(v[6], v[7]); return w; }
; #define xor16_32(s) xor16_32_l((s), fr + 16 * fq)
;     DI void operator()(AccRef acc, const Unit& u, int wr, int wc, int fr, int fq) const {
;     ...
;             for (int m = 0; m < 4; ++m) {
;                 const int row = rb + 16 * m;
;                 const float* xi = row < MP ? xin_p + (size_t)row * 1024 : xin_s + (size_t)(row - MP) * 1024;
;                 float s = 0.f;
; #pragma unroll
;                 for (int bj = 0; bj < 2; ++bj) {
;                     const int c = u.pn * 256 + bj * 128 + cl;
;                     float v[8];
; #pragma unroll
;                     for (int n = 0; n < 2; ++n) {
;                         const f32x4 x = *(const f32x4*)(xi + c + 4 * n);
;                         const f32x4 y = x + gt[bj][n] * acc[ai][bj][m][n];
;                         *(f32x4*)(xout + (size_t)row * 1024 + c + 4 * n) = y;
; #pragma unroll
;                         for (int j = 0; j < 4; ++j) { s += y[j] * y[j]; v[4 * n + j] = ap ? y[j] * gs[bj][n][j] : 0.f; }
;                     }
;                     if (ap) *(u32x4*)(ap + (size_t)row * 1024 + c) = pack8(v);
;                 }
;                 s = xor16_32(s);
;                 if (fq == 0) ssq[(size_t)row * 16 + u.pn * 4 + wc] = s;
	v_pk_mul_f32 v[218:219], v[148:149], v[114:115]
	v_pk_fma_f32 v[96:97], v[96:97], v[100:101], v[220:221]
	v_pk_fma_f32 v[98:99], v[98:99], v[102:103], v[222:223]
	v_fmac_f32_e32 v210, v96, v96
	v_fmac_f32_e32 v210, v97, v97
	v_fmac_f32_e32 v210, v98, v98
	v_fmac_f32_e32 v210, v99, v99
	v_pk_mul_f32 v[220:221], v[144:145], v[96:97]
	v_pk_mul_f32 v[222:223], v[146:147], v[98:99]
	v_cvt_pk_bf16_f32 v216, v216, v217
	v_cvt_pk_bf16_f32 v217, v218, v219
	v_cvt_pk_bf16_f32 v218, v220, v221
	v_cvt_pk_bf16_f32 v219, v222, v223
	global_store_dwordx4 v208, v[216:219], s[64:65] offset:256
	ds_bpermute_b32 v211, v203, v210
	v_permlane16_swap_b32_e32 v124, v120
	v_permlane16_swap_b32_e32 v125, v121
	v_permlane16_swap_b32_e32 v126, v122
	v_permlane16_swap_b32_e32 v127, v123
	v_permlane16_swap_b32_e32 v112, v96
	v_permlane16_swap_b32_e32 v113, v97
	v_permlane16_swap_b32_e32 v114, v98
	v_permlane16_swap_b32_e32 v115, v99
	v_permlane32_swap_b32_e32 v124, v120
	v_permlane32_swap_b32_e32 v125, v121
	v_permlane32_swap_b32_e32 v126, v122
	v_permlane32_swap_b32_e32 v127, v123
	v_permlane32_swap_b32_e32 v112, v96
	v_permlane32_swap_b32_e32 v113, v97
	v_permlane32_swap_b32_e32 v114, v98
	v_permlane32_swap_b32_e32 v115, v99
	global_store_dwordx4 v207, v[124:127], s[92:93]
	global_store_dwordx4 v207, v[120:123], s[92:93] offset:64
	global_store_dwordx4 v207, v[112:115], s[92:93] offset:512
	global_store_dwordx4 v207, v[96:99], s[92:93] offset:576
	v_add_u32_e32 v207, 0x10000, v207
	v_add_u32_e32 v206, 0x10000, v206
	global_load_dwordx4 v[248:251], v206, s[82:83] offset:64
	global_load_dwordx4 v[220:223], v206, s[82:83] offset:576
	global_load_dwordx4 v[244:247], v206, s[82:83]
	global_load_dwordx4 v[216:219], v206, s[82:83] offset:512
	s_waitcnt lgkmcnt(0)
	v_add_f32_e32 v211, v210, v211
	ds_bpermute_b32 v212, v202, v211
	v_add_u32_e32 v208, 0x8000, v208
	s_waitcnt lgkmcnt(0)
	v_add_f32_e32 v211, v211, v212
	s_mov_b64 exec, 0xffff
	global_store_dword v209, v211, s[90:91]
	s_mov_b64 exec, -1
	v_add_u32_e32 v209, 0x400, v209
	s_waitcnt vmcnt(12)
	v_permlane32_swap_b32_e32 v228, v232
	v_permlane32_swap_b32_e32 v229, v233
	v_permlane32_swap_b32_e32 v230, v234
	v_permlane32_swap_b32_e32 v231, v235
	v_permlane32_swap_b32_e32 v236, v240
	v_permlane32_swap_b32_e32 v237, v241
	v_permlane32_swap_b32_e32 v238, v242
	v_permlane32_swap_b32_e32 v239, v243
	v_permlane16_swap_b32_e32 v228, v232
	v_permlane16_swap_b32_e32 v229, v233
	v_permlane16_swap_b32_e32 v230, v234
	v_permlane16_swap_b32_e32 v231, v235
	v_permlane16_swap_b32_e32 v236, v240
	v_permlane16_swap_b32_e32 v237, v241
	v_permlane16_swap_b32_e32 v238, v242
	v_permlane16_swap_b32_e32 v239, v243
	v_pk_fma_f32 v[92:93], v[92:93], v[116:117], v[228:229]
	v_pk_fma_f32 v[94:95], v[94:95], v[118:119], v[230:231]
	v_mul_f32_e32 v210, v93, v93
	v_fmac_f32_e32 v210, v92, v92
	v_fmac_f32_e32 v210, v94, v94
	v_fmac_f32_e32 v210, v95, v95
	v_pk_mul_f32 v[228:229], v[164:165], v[92:93]
	v_pk_mul_f32 v[230:231], v[166:167], v[94:95]
	v_pk_fma_f32 v[88:89], v[88:89], v[108:109], v[232:233]
	v_pk_fma_f32 v[90:91], v[90:91], v[110:111], v[234:235]
	v_fmac_f32_e32 v210, v88, v88
	v_fmac_f32_e32 v210, v89, v89
	v_fmac_f32_e32 v210, v90, v90
	v_fmac_f32_e32 v210, v91, v91
	v_pk_mul_f32 v[232:233], v[162:163], v[88:89]
	v_pk_mul_f32 v[234:235], v[160:161], v[90:91]
	v_cvt_pk_bf16_f32 v228, v228, v229
	v_cvt_pk_bf16_f32 v229, v230, v231
	v_cvt_pk_bf16_f32 v230, v232, v233
	v_cvt_pk_bf16_f32 v231, v234, v235
	global_store_dwordx4 v208, v[228:231], s[64:65]
	v_pk_fma_f32 v[84:85], v[84:85], v[104:105], v[236:237]
	v_pk_fma_f32 v[86:87], v[86:87], v[106:107], v[238:239]
	v_fmac_f32_e32 v210, v84, v84
	v_fmac_f32_e32 v210, v85, v85
	v_fmac_f32_e32 v210, v86, v86
	v_fmac_f32_e32 v210, v87, v87
	v_pk_mul_f32 v[236:237], v[150:151], v[84:85]
	v_pk_mul_f32 v[238:239], v[148:149], v[86:87]
	v_pk_fma_f32 v[80:81], v[80:81], v[100:101], v[240:241]
	v_pk_fma_f32 v[82:83], v[82:83], v[102:103], v[242:243]
	v_fmac_f32_e32 v210, v80, v80
	v_fmac_f32_e32 v210, v81, v81
	v_fmac_f32_e32 v210, v82, v82
	v_fmac_f32_e32 v210, v83, v83
	v_pk_mul_f32 v[240:241], v[144:145], v[80:81]
	v_pk_mul_f32 v[242:243], v[146:147], v[82:83]
	v_cvt_pk_bf16_f32 v236, v236, v237
	v_cvt_pk_bf16_f32 v237, v238, v239
	v_cvt_pk_bf16_f32 v238, v240, v241
	v_cvt_pk_bf16_f32 v239, v242, v243
	global_store_dwordx4 v208, v[236:239], s[64:65] offset:256
	ds_bpermute_b32 v211, v203, v210
	v_permlane16_swap_b32_e32 v92, v88
	v_permlane16_swap_b32_e32 v93, v89
	v_permlane16_swap_b32_e32 v94, v90
	v_permlane16_swap_b32_e32 v95, v91
	v_permlane16_swap_b32_e32 v84, v80
	v_permlane16_swap_b32_e32 v85, v81
	v_permlane16_swap_b32_e32 v86, v82
	v_permlane16_swap_b32_e32 v87, v83
	v_permlane32_swap_b32_e32 v92, v88
	v_permlane32_swap_b32_e32 v93, v89
	v_permlane32_swap_b32_e32 v94, v90
	v_permlane32_swap_b32_e32 v95, v91
	v_permlane32_swap_b32_e32 v84, v80
	v_permlane32_swap_b32_e32 v85, v81
	v_permlane32_swap_b32_e32 v86, v82
	v_permlane32_swap_b32_e32 v87, v83
	global_store_dwordx4 v207, v[92:95], s[92:93]
	global_store_dwordx4 v207, v[88:91], s[92:93] offset:64
	global_store_dwordx4 v207, v[84:87], s[92:93] offset:512
	global_store_dwordx4 v207, v[80:83], s[92:93] offset:576
	v_add_u32_e32 v207, 0x10000, v207
	v_add_u32_e32 v206, 0x50000, v206
	global_load_dwordx4 v[232:235], v206, s[82:83] offset:64
	global_load_dwordx4 v[240:243], v206, s[82:83] offset:576
	global_load_dwordx4 v[228:231], v206, s[82:83]
	global_load_dwordx4 v[236:239], v206, s[82:83] offset:512
	s_waitcnt lgkmcnt(0)
	v_add_f32_e32 v211, v210, v211
	ds_bpermute_b32 v212, v202, v211
	v_add_u32_e32 v208, 0x8000, v208
	s_waitcnt lgkmcnt(0)
; DI u32x4 pack8(const float* v) { u32x4 w; w.x = pk2(v[0], v[1]); w.y = pk2(v[2], v[3]); w.z = pk2(v[4], v[5]); w.w = pk2(v[6], v[7]); return w; }
; #define xor16_32(s) xor16_32_l((s), fr + 16 * fq)
;     DI void operator()(AccRef acc, const Unit& u, int wr, int wc, int fr, int fq) const {
;     ...
;         for (int ai = 0; ai < 2; ++ai) {
;             const int rb = u.pm * 256 + ai * 128 + wr * 64 + fr;
;             int mb, pos0, kv0; row_info(rb, mb, pos0, kv0);
;             f32x4 gt[2][2], gs[2][2];
; #pragma unroll
;             for (int bj = 0; bj < 2; ++bj)
; #pragma unroll
;                 for (int n = 0; n < 2; ++n) {
;                     const int c = u.pn * 256 + bj * 128 + cl + 4 * n;
;                     gt[bj][n] = *(const f32x4*)(gate + (size_t)mb * 6144 + c);
;                     if (ap) { const f32x4 g = *(const f32x4*)(gn + c), s = *(const f32x4*)(scn + (size_t)mb * 6144 + c); gs[bj][n] = g * (s + 1.f); }
;     ...
;             for (int m = 0; m < 4; ++m) {
;                 const int row = rb + 16 * m;
;                 const float* xi = row < MP ? xin_p + (size_t)row * 1024 : xin_s + (size_t)(row - MP) * 1024;
;                 float s = 0.f;
; #pragma unroll
;                 for (int bj = 0; bj < 2; ++bj) {
;                     const int c = u.pn * 256 + bj * 128 + cl;
;                     float v[8];
; #pragma unroll
;                     for (int n = 0; n < 2; ++n) {
;                         const f32x4 x = *(const f32x4*)(xi + c + 4 * n);
;                         const f32x4 y = x + gt[bj][n] * acc[ai][bj][m][n];
;                         *(f32x4*)(xout + (size_t)row * 1024 + c + 4 * n) = y;
; #pragma unroll
;                         for (int j = 0; j < 4; ++j) { s += y[j] * y[j]; v[4 * n + j] = ap ? y[j] * gs[bj][n][j] : 0.f; }
;                     }
;                     if (ap) *(u32x4*)(ap + (size_t)row * 1024 + c) = pack8(v);
;                 }
;                 s = xor16_32(s);
;                 if (fq == 0) ssq[(size_t)row * 16 + u.pn * 4 + wc] = s;
	v_add_f32_e32 v211, v211, v212
	s_mov_b64 exec, 0xffff
	global_store_dword v209, v211, s[90:91]
	s_mov_b64 exec, -1
	v_add_u32_e32 v209, 0x400, v209
	s_waitcnt vmcnt(12)
	v_permlane32_swap_b32_e32 v244, v248
	v_permlane32_swap_b32_e32 v245, v249
	v_permlane32_swap_b32_e32 v246, v250
	v_permlane32_swap_b32_e32 v247, v251
	v_permlane32_swap_b32_e32 v216, v220
	v_permlane32_swap_b32_e32 v217, v221
	v_permlane32_swap_b32_e32 v218, v222
	v_permlane32_swap_b32_e32 v219, v223
	v_permlane16_swap_b32_e32 v244, v248
	v_permlane16_swap_b32_e32 v245, v249
	v_permlane16_swap_b32_e32 v246, v250
	v_permlane16_swap_b32_e32 v247, v251
	v_permlane16_swap_b32_e32 v216, v220
	v_permlane16_swap_b32_e32 v217, v221
	v_permlane16_swap_b32_e32 v218, v222
	v_permlane16_swap_b32_e32 v219, v223
	v_pk_fma_f32 v[76:77], v[76:77], v[116:117], v[244:245]
	v_pk_fma_f32 v[78:79], v[78:79], v[118:119], v[246:247]
	v_mul_f32_e32 v210, v77, v77
	v_fmac_f32_e32 v210, v76, v76
	v_fmac_f32_e32 v210, v78, v78
	v_fmac_f32_e32 v210, v79, v79
	v_pk_mul_f32 v[244:245], v[164:165], v[76:77]
	v_pk_mul_f32 v[246:247], v[166:167], v[78:79]
	v_pk_fma_f32 v[72:73], v[72:73], v[108:109], v[248:249]
	v_pk_fma_f32 v[74:75], v[74:75], v[110:111], v[250:251]
	v_fmac_f32_e32 v210, v72, v72
	v_fmac_f32_e32 v210, v73, v73
	v_fmac_f32_e32 v210, v74, v74
	v_fmac_f32_e32 v210, v75, v75
	v_pk_mul_f32 v[248:249], v[162:163], v[72:73]
	v_pk_mul_f32 v[250:251], v[160:161], v[74:75]
	v_cvt_pk_bf16_f32 v244, v244, v245
	v_cvt_pk_bf16_f32 v245, v246, v247
	v_cvt_pk_bf16_f32 v246, v248, v249
	v_cvt_pk_bf16_f32 v247, v250, v251
	global_store_dwordx4 v208, v[244:247], s[64:65]
	v_pk_fma_f32 v[68:69], v[68:69], v[104:105], v[216:217]
	v_pk_fma_f32 v[70:71], v[70:71], v[106:107], v[218:219]
	v_fmac_f32_e32 v210, v68, v68
	v_fmac_f32_e32 v210, v69, v69
	v_fmac_f32_e32 v210, v70, v70
	v_fmac_f32_e32 v210, v71, v71
	v_pk_mul_f32 v[216:217], v[150:151], v[68:69]
	v_pk_mul_f32 v[218:219], v[148:149], v[70:71]
	v_pk_fma_f32 v[64:65], v[64:65], v[100:101], v[220:221]
	v_pk_fma_f32 v[66:67], v[66:67], v[102:103], v[222:223]
	v_fmac_f32_e32 v210, v64, v64
	v_fmac_f32_e32 v210, v65, v65
	v_fmac_f32_e32 v210, v66, v66
	v_fmac_f32_e32 v210, v67, v67
	v_pk_mul_f32 v[220:221], v[144:145], v[64:65]
	v_pk_mul_f32 v[222:223], v[146:147], v[66:67]
	v_cvt_pk_bf16_f32 v216, v216, v217
	v_cvt_pk_bf16_f32 v217, v218, v219
	v_cvt_pk_bf16_f32 v218, v220, v221
	v_cvt_pk_bf16_f32 v219, v222, v223
	global_store_dwordx4 v208, v[216:219], s[64:65] offset:256
	ds_bpermute_b32 v211, v203, v210
	v_permlane16_swap_b32_e32 v76, v72
	v_permlane16_swap_b32_e32 v77, v73
	v_permlane16_swap_b32_e32 v78, v74
	v_permlane16_swap_b32_e32 v79, v75
	v_permlane16_swap_b32_e32 v68, v64
	v_permlane16_swap_b32_e32 v69, v65
	v_permlane16_swap_b32_e32 v70, v66
	v_permlane16_swap_b32_e32 v71, v67
	v_permlane32_swap_b32_e32 v76, v72
	v_permlane32_swap_b32_e32 v77, v73
	v_permlane32_swap_b32_e32 v78, v74
	v_permlane32_swap_b32_e32 v79, v75
	v_permlane32_swap_b32_e32 v68, v64
	v_permlane32_swap_b32_e32 v69, v65
	v_permlane32_swap_b32_e32 v70, v66
	v_permlane32_swap_b32_e32 v71, v67
	global_store_dwordx4 v207, v[76:79], s[92:93]
	global_store_dwordx4 v207, v[72:75], s[92:93] offset:64
	global_store_dwordx4 v207, v[68:71], s[92:93] offset:512
	global_store_dwordx4 v207, v[64:67], s[92:93] offset:576
	v_add_u32_e32 v207, 0x50000, v207
	v_add_u32_e32 v206, 0x10000, v206
	global_load_dwordx4 v[248:251], v206, s[82:83] offset:64
	global_load_dwordx4 v[220:223], v206, s[82:83] offset:576
	global_load_dwordx4 v[244:247], v206, s[82:83]
	global_load_dwordx4 v[216:219], v206, s[82:83] offset:512
	s_waitcnt lgkmcnt(0)
	v_add_f32_e32 v211, v210, v211
	ds_bpermute_b32 v212, v202, v211
	v_add_u32_e32 v208, 0x28000, v208
	s_waitcnt lgkmcnt(0)
	v_add_f32_e32 v211, v211, v212
	s_mov_b64 exec, 0xffff
	global_store_dword v209, v211, s[90:91]
	s_mov_b64 exec, -1
	v_add_u32_e32 v209, 0x1400, v209
	v_add_u32_e32 v224, 0xffffc080, v192
	v_add_u32_e32 v112, 0x80, v192
	s_waitcnt lgkmcnt(0)
	v_lshrrev_b32_e32 v65, 6, v224
	v_ashrrev_i32_e32 v64, 11, v112
	v_add_u32_e32 v65, 8, v65
	v_cmp_gt_i32_e64 s[2:3], s94, v112
	v_mov_b64_e32 v[66:67], s[60:61]
	s_nop 0
	v_cndmask_b32_e64 v68, v65, v64, s[2:3]
	v_mov_b64_e32 v[64:65], s[8:9]
	v_mad_i64_i32 v[64:65], s[2:3], v68, s75, v[64:65]
	v_mad_i64_i32 v[66:67], s[2:3], v68, s75, v[66:67]
	v_lshl_add_u64 v[68:69], v[64:65], 0, v[190:191]
	v_lshl_add_u64 v[104:105], v[66:67], 0, v[190:191]
	global_load_dwordx4 v[72:75], v[68:69], off offset:16
	global_load_dwordx4 v[76:79], v[68:69], off
	global_load_dwordx4 v[84:87], v[194:195], off offset:16
	global_load_dwordx4 v[100:103], v[194:195], off
	global_load_dwordx4 v[96:99], v[104:105], off offset:16
	global_load_dwordx4 v[108:111], v[104:105], off
	global_load_dwordx4 v[64:67], v[68:69], off offset:528
	s_nop 0
	global_load_dwordx4 v[68:71], v[68:69], off offset:512
	s_nop 0
	global_load_dwordx4 v[80:83], v[194:195], off offset:528
	global_load_dwordx4 v[92:95], v[194:195], off offset:512
	global_load_dwordx4 v[88:91], v[104:105], off offset:528
	s_nop 0
	global_load_dwordx4 v[104:107], v[104:105], off offset:512
	s_movk_i32 s2, 0x3fff
	v_cmp_lt_i32_e64 s[2:3], s2, v112
	s_and_saveexec_b64 s[12:13], s[2:3]
	s_xor_b64 s[2:3], exec, s[12:13]
	v_lshlrev_b64 v[114:115], 12, v[224:225]
	v_mov_b32_e32 v113, v225
	v_lshl_add_u64 v[116:117], s[20:21], 0, v[114:115]
	v_lshlrev_b64 v[114:115], 12, v[112:113]
	s_andn2_saveexec_b64 s[2:3], s[2:3]
	v_ashrrev_i32_e32 v113, 31, v112
	v_lshlrev_b64 v[114:115], 12, v[112:113]
	v_lshl_add_u64 v[116:117], s[42:43], 0, v[114:115]
	s_or_b64 exec, exec, s[2:3]
	s_waitcnt vmcnt(6)
; DI u32x4 pack8(const float* v) { u32x4 w; w.x = pk2(v[0], v[1]); w.y = pk2(v[2], v[3]); w.z = pk2(v[4], v[5]); w.w = pk2(v[6], v[7]); return w; }
; #define xor16_32(s) xor16_32_l((s), fr + 16 * fq)
;     DI void operator()(AccRef acc, const Unit& u, int wr, int wc, int fr, int fq) const {
;     ...
;                     if (ap) { const f32x4 g = *(const f32x4*)(gn + c), s = *(const f32x4*)(scn + (size_t)mb * 6144 + c); gs[bj][n] = g * (s + 1.f); }
;                 }
; #pragma unroll
;             for (int m = 0; m < 4; ++m) {
;                 const int row = rb + 16 * m;
;                 const float* xi = row < MP ? xin_p + (size_t)row * 1024 : xin_s + (size_t)(row - MP) * 1024;
;                 float s = 0.f;
; #pragma unroll
;                 for (int bj = 0; bj < 2; ++bj) {
;                     const int c = u.pn * 256 + bj * 128 + cl;
;                     float v[8];
; #pragma unroll
;                     for (int n = 0; n < 2; ++n) {
;                         const f32x4 x = *(const f32x4*)(xi + c + 4 * n);
;                         const f32x4 y = x + gt[bj][n] * acc[ai][bj][m][n];
;                         *(f32x4*)(xout + (size_t)row * 1024 + c + 4 * n) = y;
; #pragma unroll
;                         for (int j = 0; j < 4; ++j) { s += y[j] * y[j]; v[4 * n + j] = ap ? y[j] * gs[bj][n][j] : 0.f; }
;                     }
;                     if (ap) *(u32x4*)(ap + (size_t)row * 1024 + c) = pack8(v);
;                 }
;                 s = xor16_32(s);
;                 if (fq == 0) ssq[(size_t)row * 16 + u.pn * 4 + wc] = s;
	v_pk_add_f32 v[108:109], v[108:109], 1.0 op_sel_hi:[1,0]
	s_waitcnt vmcnt(1)
	v_pk_add_f32 v[90:91], v[90:91], 1.0 op_sel_hi:[1,0]
	v_pk_mul_f32 v[100:101], v[100:101], v[108:109]
	v_pk_add_f32 v[108:109], v[96:97], 1.0 op_sel_hi:[1,0]
	v_pk_add_f32 v[96:97], v[98:99], 1.0 op_sel_hi:[1,0]
	v_pk_mul_f32 v[98:99], v[84:85], v[108:109]
	v_pk_mul_f32 v[96:97], v[86:87], v[96:97]
	s_waitcnt vmcnt(0)
	v_pk_add_f32 v[84:85], v[106:107], 1.0 op_sel_hi:[1,0]
	v_pk_add_f32 v[86:87], v[104:105], 1.0 op_sel_hi:[1,0]
	v_pk_mul_f32 v[82:83], v[82:83], v[90:91]
	v_lshl_add_u64 v[90:91], v[116:117], 0, v[190:191]
	v_pk_mul_f32 v[84:85], v[94:95], v[84:85]
	v_pk_mul_f32 v[86:87], v[92:93], v[86:87]
	v_pk_add_f32 v[110:111], v[110:111], 1.0 op_sel_hi:[1,0]
	v_pk_add_f32 v[88:89], v[88:89], 1.0 op_sel_hi:[1,0]
	v_pk_mul_f32 v[102:103], v[102:103], v[110:111]
	v_pk_mul_f32 v[80:81], v[80:81], v[88:89]
	v_lshlrev_b64 v[88:89], 11, v[112:113]
	v_lshl_add_u64 v[88:89], s[64:65], 0, v[88:89]
	v_permlane32_swap_b32_e32 v228, v232
	v_permlane32_swap_b32_e32 v229, v233
	v_permlane32_swap_b32_e32 v230, v234
	v_permlane32_swap_b32_e32 v231, v235
	v_permlane32_swap_b32_e32 v236, v240
	v_permlane32_swap_b32_e32 v237, v241
	v_permlane32_swap_b32_e32 v238, v242
	v_permlane32_swap_b32_e32 v239, v243
	v_permlane16_swap_b32_e32 v228, v232
	v_permlane16_swap_b32_e32 v229, v233
	v_permlane16_swap_b32_e32 v230, v234
	v_permlane16_swap_b32_e32 v231, v235
	v_permlane16_swap_b32_e32 v236, v240
	v_permlane16_swap_b32_e32 v237, v241
	v_permlane16_swap_b32_e32 v238, v242
	v_permlane16_swap_b32_e32 v239, v243
	v_pk_fma_f32 v[60:61], v[60:61], v[76:77], v[228:229]
	v_pk_fma_f32 v[62:63], v[62:63], v[78:79], v[230:231]
	v_mul_f32_e32 v210, v61, v61
	v_fmac_f32_e32 v210, v60, v60
	v_fmac_f32_e32 v210, v62, v62
	v_fmac_f32_e32 v210, v63, v63
	v_pk_mul_f32 v[228:229], v[100:101], v[60:61]
	v_pk_mul_f32 v[230:231], v[102:103], v[62:63]
	v_pk_fma_f32 v[56:57], v[56:57], v[72:73], v[232:233]
	v_pk_fma_f32 v[58:59], v[58:59], v[74:75], v[234:235]
	v_fmac_f32_e32 v210, v56, v56
	v_fmac_f32_e32 v210, v57, v57
	v_fmac_f32_e32 v210, v58, v58
	v_fmac_f32_e32 v210, v59, v59
	v_pk_mul_f32 v[232:233], v[98:99], v[56:57]
	v_pk_mul_f32 v[234:235], v[96:97], v[58:59]
	v_cvt_pk_bf16_f32 v228, v228, v229
	v_cvt_pk_bf16_f32 v229, v230, v231
	v_cvt_pk_bf16_f32 v230, v232, v233
	v_cvt_pk_bf16_f32 v231, v234, v235
	global_store_dwordx4 v208, v[228:231], s[64:65]
	v_pk_fma_f32 v[52:53], v[52:53], v[68:69], v[236:237]
	v_pk_fma_f32 v[54:55], v[54:55], v[70:71], v[238:239]
	v_fmac_f32_e32 v210, v52, v52
	v_fmac_f32_e32 v210, v53, v53
	v_fmac_f32_e32 v210, v54, v54
	v_fmac_f32_e32 v210, v55, v55
	v_pk_mul_f32 v[236:237], v[86:87], v[52:53]
	v_pk_mul_f32 v[238:239], v[84:85], v[54:55]
	v_pk_fma_f32 v[48:49], v[48:49], v[64:65], v[240:241]
	v_pk_fma_f32 v[50:51], v[50:51], v[66:67], v[242:243]
	v_fmac_f32_e32 v210, v48, v48
	v_fmac_f32_e32 v210, v49, v49
	v_fmac_f32_e32 v210, v50, v50
	v_fmac_f32_e32 v210, v51, v51
	v_pk_mul_f32 v[240:241], v[80:81], v[48:49]
	v_pk_mul_f32 v[242:243], v[82:83], v[50:51]
	v_cvt_pk_bf16_f32 v236, v236, v237
	v_cvt_pk_bf16_f32 v237, v238, v239
	v_cvt_pk_bf16_f32 v238, v240, v241
	v_cvt_pk_bf16_f32 v239, v242, v243
	global_store_dwordx4 v208, v[236:239], s[64:65] offset:256
	ds_bpermute_b32 v211, v203, v210
	v_permlane16_swap_b32_e32 v60, v56
	v_permlane16_swap_b32_e32 v61, v57
	v_permlane16_swap_b32_e32 v62, v58
	v_permlane16_swap_b32_e32 v63, v59
	v_permlane16_swap_b32_e32 v52, v48
	v_permlane16_swap_b32_e32 v53, v49
	v_permlane16_swap_b32_e32 v54, v50
	v_permlane16_swap_b32_e32 v55, v51
	v_permlane32_swap_b32_e32 v60, v56
	v_permlane32_swap_b32_e32 v61, v57
	v_permlane32_swap_b32_e32 v62, v58
	v_permlane32_swap_b32_e32 v63, v59
	v_permlane32_swap_b32_e32 v52, v48
	v_permlane32_swap_b32_e32 v53, v49
	v_permlane32_swap_b32_e32 v54, v50
	v_permlane32_swap_b32_e32 v55, v51
	global_store_dwordx4 v207, v[60:63], s[92:93]
	global_store_dwordx4 v207, v[56:59], s[92:93] offset:64
	global_store_dwordx4 v207, v[52:55], s[92:93] offset:512
	global_store_dwordx4 v207, v[48:51], s[92:93] offset:576
	v_add_u32_e32 v207, 0x10000, v207
	v_add_u32_e32 v206, 0x10000, v206
	global_load_dwordx4 v[232:235], v206, s[82:83] offset:64
	global_load_dwordx4 v[240:243], v206, s[82:83] offset:576
	global_load_dwordx4 v[228:231], v206, s[82:83]
	global_load_dwordx4 v[236:239], v206, s[82:83] offset:512
	s_waitcnt lgkmcnt(0)
	v_add_f32_e32 v211, v210, v211
	ds_bpermute_b32 v212, v202, v211
	v_add_u32_e32 v208, 0x8000, v208
	s_waitcnt lgkmcnt(0)
; DI u32x4 pack8(const float* v) { u32x4 w; w.x = pk2(v[0], v[1]); w.y = pk2(v[2], v[3]); w.z = pk2(v[4], v[5]); w.w = pk2(v[6], v[7]); return w; }
; #define xor16_32(s) xor16_32_l((s), fr + 16 * fq)
;     DI void operator()(AccRef acc, const Unit& u, int wr, int wc, int fr, int fq) const {
;     ...
;             for (int m = 0; m < 4; ++m) {
;                 const int row = rb + 16 * m;
;                 const float* xi = row < MP ? xin_p + (size_t)row * 1024 : xin_s + (size_t)(row - MP) * 1024;
;                 float s = 0.f;
; #pragma unroll
;                 for (int bj = 0; bj < 2; ++bj) {
;                     const int c = u.pn * 256 + bj * 128 + cl;
;                     float v[8];
; #pragma unroll
;                     for (int n = 0; n < 2; ++n) {
;                         const f32x4 x = *(const f32x4*)(xi + c + 4 * n);
;                         const f32x4 y = x + gt[bj][n] * acc[ai][bj][m][n];
;                         *(f32x4*)(xout + (size_t)row * 1024 + c + 4 * n) = y;
; #pragma unroll
;                         for (int j = 0; j < 4; ++j) { s += y[j] * y[j]; v[4 * n + j] = ap ? y[j] * gs[bj][n][j] : 0.f; }
;                     }
;                     if (ap) *(u32x4*)(ap + (size_t)row * 1024 + c) = pack8(v);
;                 }
;                 s = xor16_32(s);
;                 if (fq == 0) ssq[(size_t)row * 16 + u.pn * 4 + wc] = s;
	v_add_f32_e32 v211, v211, v212
	s_mov_b64 exec, 0xffff
	global_store_dword v209, v211, s[90:91]
	s_mov_b64 exec, -1
	v_add_u32_e32 v209, 0x400, v209
	v_permlane32_swap_b32_e32 v244, v248
	v_permlane32_swap_b32_e32 v245, v249
	v_permlane32_swap_b32_e32 v246, v250
	v_permlane32_swap_b32_e32 v247, v251
	v_permlane32_swap_b32_e32 v216, v220
	v_permlane32_swap_b32_e32 v217, v221
	v_permlane32_swap_b32_e32 v218, v222
	v_permlane32_swap_b32_e32 v219, v223
	v_permlane16_swap_b32_e32 v244, v248
	v_permlane16_swap_b32_e32 v245, v249
	v_permlane16_swap_b32_e32 v246, v250
	v_permlane16_swap_b32_e32 v247, v251
	v_permlane16_swap_b32_e32 v216, v220
	v_permlane16_swap_b32_e32 v217, v221
	v_permlane16_swap_b32_e32 v218, v222
	v_permlane16_swap_b32_e32 v219, v223
	v_pk_fma_f32 v[44:45], v[44:45], v[76:77], v[244:245]
	v_pk_fma_f32 v[46:47], v[46:47], v[78:79], v[246:247]
	v_mul_f32_e32 v210, v45, v45
	v_fmac_f32_e32 v210, v44, v44
	v_fmac_f32_e32 v210, v46, v46
	v_fmac_f32_e32 v210, v47, v47
	v_pk_mul_f32 v[244:245], v[100:101], v[44:45]
	v_pk_mul_f32 v[246:247], v[102:103], v[46:47]
	v_pk_fma_f32 v[40:41], v[40:41], v[72:73], v[248:249]
	v_pk_fma_f32 v[42:43], v[42:43], v[74:75], v[250:251]
	v_fmac_f32_e32 v210, v40, v40
	v_fmac_f32_e32 v210, v41, v41
	v_fmac_f32_e32 v210, v42, v42
	v_fmac_f32_e32 v210, v43, v43
	v_pk_mul_f32 v[248:249], v[98:99], v[40:41]
	v_pk_mul_f32 v[250:251], v[96:97], v[42:43]
	v_cvt_pk_bf16_f32 v244, v244, v245
	v_cvt_pk_bf16_f32 v245, v246, v247
	v_cvt_pk_bf16_f32 v246, v248, v249
	v_cvt_pk_bf16_f32 v247, v250, v251
	global_store_dwordx4 v208, v[244:247], s[64:65]
	v_pk_fma_f32 v[36:37], v[36:37], v[68:69], v[216:217]
	v_pk_fma_f32 v[38:39], v[38:39], v[70:71], v[218:219]
	v_fmac_f32_e32 v210, v36, v36
	v_fmac_f32_e32 v210, v37, v37
	v_fmac_f32_e32 v210, v38, v38
	v_fmac_f32_e32 v210, v39, v39
	v_pk_mul_f32 v[216:217], v[86:87], v[36:37]
	v_pk_mul_f32 v[218:219], v[84:85], v[38:39]
	v_pk_fma_f32 v[32:33], v[32:33], v[64:65], v[220:221]
	v_pk_fma_f32 v[34:35], v[34:35], v[66:67], v[222:223]
	v_fmac_f32_e32 v210, v32, v32
	v_fmac_f32_e32 v210, v33, v33
	v_fmac_f32_e32 v210, v34, v34
	v_fmac_f32_e32 v210, v35, v35
	v_pk_mul_f32 v[220:221], v[80:81], v[32:33]
	v_pk_mul_f32 v[222:223], v[82:83], v[34:35]
	v_cvt_pk_bf16_f32 v216, v216, v217
	v_cvt_pk_bf16_f32 v217, v218, v219
	v_cvt_pk_bf16_f32 v218, v220, v221
	v_cvt_pk_bf16_f32 v219, v222, v223
	global_store_dwordx4 v208, v[216:219], s[64:65] offset:256
	ds_bpermute_b32 v211, v203, v210
	v_permlane16_swap_b32_e32 v44, v40
	v_permlane16_swap_b32_e32 v45, v41
	v_permlane16_swap_b32_e32 v46, v42
	v_permlane16_swap_b32_e32 v47, v43
	v_permlane16_swap_b32_e32 v36, v32
	v_permlane16_swap_b32_e32 v37, v33
	v_permlane16_swap_b32_e32 v38, v34
	v_permlane16_swap_b32_e32 v39, v35
	v_permlane32_swap_b32_e32 v44, v40
	v_permlane32_swap_b32_e32 v45, v41
	v_permlane32_swap_b32_e32 v46, v42
	v_permlane32_swap_b32_e32 v47, v43
	v_permlane32_swap_b32_e32 v36, v32
	v_permlane32_swap_b32_e32 v37, v33
	v_permlane32_swap_b32_e32 v38, v34
	v_permlane32_swap_b32_e32 v39, v35
	global_store_dwordx4 v207, v[44:47], s[92:93]
	global_store_dwordx4 v207, v[40:43], s[92:93] offset:64
	global_store_dwordx4 v207, v[36:39], s[92:93] offset:512
	global_store_dwordx4 v207, v[32:35], s[92:93] offset:576
	v_add_u32_e32 v207, 0x10000, v207
	v_add_u32_e32 v206, 0x10000, v206
	global_load_dwordx4 v[248:251], v206, s[82:83] offset:64
	global_load_dwordx4 v[220:223], v206, s[82:83] offset:576
	global_load_dwordx4 v[244:247], v206, s[82:83]
	global_load_dwordx4 v[216:219], v206, s[82:83] offset:512
	s_waitcnt lgkmcnt(0)
	v_add_f32_e32 v211, v210, v211
	ds_bpermute_b32 v212, v202, v211
	v_add_u32_e32 v208, 0x8000, v208
	s_waitcnt lgkmcnt(0)
	v_add_f32_e32 v211, v211, v212
	s_mov_b64 exec, 0xffff
	global_store_dword v209, v211, s[90:91]
	s_mov_b64 exec, -1
	v_add_u32_e32 v209, 0x400, v209
	s_waitcnt vmcnt(12)
; DI u32x4 pack8(const float* v) { u32x4 w; w.x = pk2(v[0], v[1]); w.y = pk2(v[2], v[3]); w.z = pk2(v[4], v[5]); w.w = pk2(v[6], v[7]); return w; }
; #define xor16_32(s) xor16_32_l((s), fr + 16 * fq)
; #define otid() otid_w(g_wave)
; #define PG8_BAR __builtin_amdgcn_s_barrier()
; template <class Epi, bool ALIGN_EPI, bool SP2>
; DI void gemm_phase(int g_wave, LAS unsigned char* lds, const Gemm g, const StaticOrder& S, const Epi& E) {
;     ...
;         if constexpr (ALIGN_EPI) { if (wr == 0) PG8_BAR; }
;         { const int t2_ = otid(); int fr_ = t2_ & 15, fq_ = (t2_ >> 4) & 3, wr_ = wr, wc_ = wc; asm volatile("" : "+v"(fr_), "+v"(fq_), "+s"(wr_), "+s"(wc_)); E(acc, cur, wr_, wc_, fr_, fq_); }
;         if (!has_next) break;
; #pragma unroll
;         for (int a = 0; a < 2; ++a)
; #pragma unroll
;             for (int b = 0; b < 2; ++b)
; #pragma unroll
;                 for (int m = 0; m < 4; ++m)
; #pragma unroll
;                     for (int n = 0; n < 2; ++n) acc[a][b][m][n] = (f32x4){0.f, 0.f, 0.f, 0.f};
;         cur = nxt; cA = nA; cB = nB; ++ui;
;         if constexpr (ALIGN_EPI) { if (wr == 1) PG8_BAR; }
;     }
;     DI void operator()(AccRef acc, const Unit& u, int wr, int wc, int fr, int fq) const {
;     ...
;             for (int m = 0; m < 4; ++m) {
;                 const int row = rb + 16 * m;
;                 const float* xi = row < MP ? xin_p + (size_t)row * 1024 : xin_s + (size_t)(row - MP) * 1024;
;                 float s = 0.f;
; #pragma unroll
;                 for (int bj = 0; bj < 2; ++bj) {
;                     const int c = u.pn * 256 + bj * 128 + cl;
;                     float v[8];
; #pragma unroll
;                     for (int n = 0; n < 2; ++n) {
;                         const f32x4 x = *(const f32x4*)(xi + c + 4 * n);
;                         const f32x4 y = x + gt[bj][n] * acc[ai][bj][m][n];
;                         *(f32x4*)(xout + (size_t)row * 1024 + c + 4 * n) = y;
; #pragma unroll
;                         for (int j = 0; j < 4; ++j) { s += y[j] * y[j]; v[4 * n + j] = ap ? y[j] * gs[bj][n][j] : 0.f; }
;                     }
;                     if (ap) *(u32x4*)(ap + (size_t)row * 1024 + c) = pack8(v);
;                 }
;                 s = xor16_32(s);
;                 if (fq == 0) ssq[(size_t)row * 16 + u.pn * 4 + wc] = s;
	v_permlane32_swap_b32_e32 v228, v232
	v_permlane32_swap_b32_e32 v229, v233
	v_permlane32_swap_b32_e32 v230, v234
	v_permlane32_swap_b32_e32 v231, v235
	v_permlane32_swap_b32_e32 v236, v240
	v_permlane32_swap_b32_e32 v237, v241
	v_permlane32_swap_b32_e32 v238, v242
	v_permlane32_swap_b32_e32 v239, v243
	v_permlane16_swap_b32_e32 v228, v232
	v_permlane16_swap_b32_e32 v229, v233
	v_permlane16_swap_b32_e32 v230, v234
	v_permlane16_swap_b32_e32 v231, v235
	v_permlane16_swap_b32_e32 v236, v240
	v_permlane16_swap_b32_e32 v237, v241
	v_permlane16_swap_b32_e32 v238, v242
	v_permlane16_swap_b32_e32 v239, v243
	v_pk_fma_f32 v[28:29], v[28:29], v[76:77], v[228:229]
	v_pk_fma_f32 v[30:31], v[30:31], v[78:79], v[230:231]
	v_mul_f32_e32 v210, v29, v29
	v_fmac_f32_e32 v210, v28, v28
	v_fmac_f32_e32 v210, v30, v30
	v_fmac_f32_e32 v210, v31, v31
	v_pk_mul_f32 v[228:229], v[100:101], v[28:29]
	v_pk_mul_f32 v[230:231], v[102:103], v[30:31]
	v_pk_fma_f32 v[24:25], v[24:25], v[72:73], v[232:233]
	v_pk_fma_f32 v[26:27], v[26:27], v[74:75], v[234:235]
	v_fmac_f32_e32 v210, v24, v24
	v_fmac_f32_e32 v210, v25, v25
	v_fmac_f32_e32 v210, v26, v26
	v_fmac_f32_e32 v210, v27, v27
	v_pk_mul_f32 v[232:233], v[98:99], v[24:25]
	v_pk_mul_f32 v[234:235], v[96:97], v[26:27]
	v_cvt_pk_bf16_f32 v228, v228, v229
	v_cvt_pk_bf16_f32 v229, v230, v231
	v_cvt_pk_bf16_f32 v230, v232, v233
	v_cvt_pk_bf16_f32 v231, v234, v235
	global_store_dwordx4 v208, v[228:231], s[64:65]
	v_pk_fma_f32 v[20:21], v[20:21], v[68:69], v[236:237]
	v_pk_fma_f32 v[22:23], v[22:23], v[70:71], v[238:239]
	v_fmac_f32_e32 v210, v20, v20
	v_fmac_f32_e32 v210, v21, v21
	v_fmac_f32_e32 v210, v22, v22
	v_fmac_f32_e32 v210, v23, v23
	v_pk_mul_f32 v[236:237], v[86:87], v[20:21]
	v_pk_mul_f32 v[238:239], v[84:85], v[22:23]
	v_pk_fma_f32 v[16:17], v[16:17], v[64:65], v[240:241]
	v_pk_fma_f32 v[18:19], v[18:19], v[66:67], v[242:243]
	v_fmac_f32_e32 v210, v16, v16
	v_fmac_f32_e32 v210, v17, v17
	v_fmac_f32_e32 v210, v18, v18
	v_fmac_f32_e32 v210, v19, v19
	v_pk_mul_f32 v[240:241], v[80:81], v[16:17]
	v_pk_mul_f32 v[242:243], v[82:83], v[18:19]
	v_cvt_pk_bf16_f32 v236, v236, v237
	v_cvt_pk_bf16_f32 v237, v238, v239
	v_cvt_pk_bf16_f32 v238, v240, v241
	v_cvt_pk_bf16_f32 v239, v242, v243
	global_store_dwordx4 v208, v[236:239], s[64:65] offset:256
	ds_bpermute_b32 v211, v203, v210
	v_permlane16_swap_b32_e32 v28, v24
	v_permlane16_swap_b32_e32 v29, v25
	v_permlane16_swap_b32_e32 v30, v26
	v_permlane16_swap_b32_e32 v31, v27
	v_permlane16_swap_b32_e32 v20, v16
	v_permlane16_swap_b32_e32 v21, v17
	v_permlane16_swap_b32_e32 v22, v18
	v_permlane16_swap_b32_e32 v23, v19
	v_permlane32_swap_b32_e32 v28, v24
	v_permlane32_swap_b32_e32 v29, v25
	v_permlane32_swap_b32_e32 v30, v26
	v_permlane32_swap_b32_e32 v31, v27
	v_permlane32_swap_b32_e32 v20, v16
	v_permlane32_swap_b32_e32 v21, v17
	v_permlane32_swap_b32_e32 v22, v18
	v_permlane32_swap_b32_e32 v23, v19
	global_store_dwordx4 v207, v[28:31], s[92:93]
	global_store_dwordx4 v207, v[24:27], s[92:93] offset:64
	global_store_dwordx4 v207, v[20:23], s[92:93] offset:512
	global_store_dwordx4 v207, v[16:19], s[92:93] offset:576
	v_add_u32_e32 v207, 0x10000, v207
	s_waitcnt lgkmcnt(0)
	v_add_f32_e32 v211, v210, v211
	ds_bpermute_b32 v212, v202, v211
	v_add_u32_e32 v208, 0x8000, v208
	s_waitcnt lgkmcnt(0)
	v_add_f32_e32 v211, v211, v212
	s_mov_b64 exec, 0xffff
	global_store_dword v209, v211, s[90:91]
	s_mov_b64 exec, -1
	v_add_u32_e32 v209, 0x400, v209
	s_waitcnt vmcnt(8)
	v_permlane32_swap_b32_e32 v244, v248
	v_permlane32_swap_b32_e32 v245, v249
	v_permlane32_swap_b32_e32 v246, v250
	v_permlane32_swap_b32_e32 v247, v251
	v_permlane32_swap_b32_e32 v216, v220
	v_permlane32_swap_b32_e32 v217, v221
	v_permlane32_swap_b32_e32 v218, v222
	v_permlane32_swap_b32_e32 v219, v223
	v_permlane16_swap_b32_e32 v244, v248
	v_permlane16_swap_b32_e32 v245, v249
	v_permlane16_swap_b32_e32 v246, v250
	v_permlane16_swap_b32_e32 v247, v251
	v_permlane16_swap_b32_e32 v216, v220
	v_permlane16_swap_b32_e32 v217, v221
	v_permlane16_swap_b32_e32 v218, v222
	v_permlane16_swap_b32_e32 v219, v223
	v_pk_fma_f32 v[12:13], v[12:13], v[76:77], v[244:245]
	v_pk_fma_f32 v[14:15], v[14:15], v[78:79], v[246:247]
	v_mul_f32_e32 v210, v13, v13
	v_fmac_f32_e32 v210, v12, v12
	v_fmac_f32_e32 v210, v14, v14
	v_fmac_f32_e32 v210, v15, v15
	v_pk_mul_f32 v[244:245], v[100:101], v[12:13]
	v_pk_mul_f32 v[246:247], v[102:103], v[14:15]
	v_pk_fma_f32 v[8:9], v[8:9], v[72:73], v[248:249]
	v_pk_fma_f32 v[10:11], v[10:11], v[74:75], v[250:251]
	v_fmac_f32_e32 v210, v8, v8
	v_fmac_f32_e32 v210, v9, v9
	v_fmac_f32_e32 v210, v10, v10
	v_fmac_f32_e32 v210, v11, v11
	v_pk_mul_f32 v[248:249], v[98:99], v[8:9]
	v_pk_mul_f32 v[250:251], v[96:97], v[10:11]
	v_cvt_pk_bf16_f32 v244, v244, v245
	v_cvt_pk_bf16_f32 v245, v246, v247
	v_cvt_pk_bf16_f32 v246, v248, v249
	v_cvt_pk_bf16_f32 v247, v250, v251
	global_store_dwordx4 v208, v[244:247], s[64:65]
	v_pk_fma_f32 v[4:5], v[4:5], v[68:69], v[216:217]
	v_pk_fma_f32 v[6:7], v[6:7], v[70:71], v[218:219]
	v_fmac_f32_e32 v210, v4, v4
	v_fmac_f32_e32 v210, v5, v5
	v_fmac_f32_e32 v210, v6, v6
	v_fmac_f32_e32 v210, v7, v7
	v_pk_mul_f32 v[216:217], v[86:87], v[4:5]
	v_pk_mul_f32 v[218:219], v[84:85], v[6:7]
	v_pk_fma_f32 v[0:1], v[0:1], v[64:65], v[220:221]
	v_pk_fma_f32 v[2:3], v[2:3], v[66:67], v[222:223]
	v_fmac_f32_e32 v210, v0, v0
	v_fmac_f32_e32 v210, v1, v1
	v_fmac_f32_e32 v210, v2, v2
	v_fmac_f32_e32 v210, v3, v3
	v_pk_mul_f32 v[220:221], v[80:81], v[0:1]
	v_pk_mul_f32 v[222:223], v[82:83], v[2:3]
	v_cvt_pk_bf16_f32 v216, v216, v217
	v_cvt_pk_bf16_f32 v217, v218, v219
	v_cvt_pk_bf16_f32 v218, v220, v221
	v_cvt_pk_bf16_f32 v219, v222, v223
	global_store_dwordx4 v208, v[216:219], s[64:65] offset:256
	ds_bpermute_b32 v211, v203, v210
	v_permlane16_swap_b32_e32 v12, v8
	v_permlane16_swap_b32_e32 v13, v9
	v_permlane16_swap_b32_e32 v14, v10
	v_permlane16_swap_b32_e32 v15, v11
	v_permlane16_swap_b32_e32 v4, v0
	v_permlane16_swap_b32_e32 v5, v1
	v_permlane16_swap_b32_e32 v6, v2
	v_permlane16_swap_b32_e32 v7, v3
	v_permlane32_swap_b32_e32 v12, v8
	v_permlane32_swap_b32_e32 v13, v9
	v_permlane32_swap_b32_e32 v14, v10
	v_permlane32_swap_b32_e32 v15, v11
	v_permlane32_swap_b32_e32 v4, v0
	v_permlane32_swap_b32_e32 v5, v1
	v_permlane32_swap_b32_e32 v6, v2
	v_permlane32_swap_b32_e32 v7, v3
	global_store_dwordx4 v207, v[12:15], s[92:93]
	global_store_dwordx4 v207, v[8:11], s[92:93] offset:64
	global_store_dwordx4 v207, v[4:7], s[92:93] offset:512
	global_store_dwordx4 v207, v[0:3], s[92:93] offset:576
	s_waitcnt lgkmcnt(0)
	v_add_f32_e32 v211, v210, v211
	ds_bpermute_b32 v212, v202, v211
	s_waitcnt lgkmcnt(0)
	v_add_f32_e32 v211, v211, v212
	s_mov_b64 exec, 0xffff
	global_store_dword v209, v211, s[90:91]
	s_mov_b64 exec, -1
	s_andn2_b64 vcc, exec, s[0:1]
	s_mov_b64 s[0:1], -1
	s_cbranch_vccnz .LBB0_1083
	s_andn2_b64 vcc, exec, s[4:5]
	s_cbranch_vccnz .LBB0_1082
	s_barrier
	s_branch .LBB0_1082

;     DI void operator()(AccRef acc, const Unit& u, int wr, int wc, int fr, int fq) const {
;     ...
; #pragma unroll
;         for (int ai = 0; ai < 2; ++ai) {
;             const int rb = u.pm * 256 + ai * 128 + wr * 64 + fr;
;             int mb, pos0, kv0; row_info(rb, mb, pos0, kv0);
;             f32x4 gt[2][2], gs[2][2];
; #pragma unroll
;             for (int bj = 0; bj < 2; ++bj)
; #pragma unroll
;                 for (int n = 0; n < 2; ++n) {
;                     const int c = u.pn * 256 + bj * 128 + cl + 4 * n;
;                     gt[bj][n] = *(const f32x4*)(gate + (size_t)mb * 6144 + c);
;                     if (ap) { const f32x4 g = *(const f32x4*)(gn + c), s = *(const f32x4*)(scn + (size_t)mb * 6144 + c); gs[bj][n] = g * (s + 1.f); }
;                 }
; #pragma unroll
;             for (int m = 0; m < 4; ++m) {
;                 const int row = rb + 16 * m;
;                 const float* xi = row < MP ? xin_p + (size_t)row * 1024 : xin_s + (size_t)(row - MP) * 1024;
;                 float s = 0.f;
; #pragma unroll
;                 for (int bj = 0; bj < 2; ++bj) {
;                     const int c = u.pn * 256 + bj * 128 + cl;
;                     float v[8];
; #pragma unroll
;                     for (int n = 0; n < 2; ++n) {
;                         const f32x4 x = *(const f32x4*)(xi + c + 4 * n);
;                         const f32x4 y = x + gt[bj][n] * acc[ai][bj][m][n];
;                         *(f32x4*)(xout + (size_t)row * 1024 + c + 4 * n) = y;
.LBB0_1303:
	v_readlane_b32 s1, v253, 32
	v_mbcnt_lo_u32_b32 v100, -1, 0
	v_mbcnt_hi_u32_b32 v100, -1, v100
	s_mov_b32 s1, s28
	v_and_b32_e32 v202, 15, v100
	v_bfe_u32 v204, v100, 4, 2
	s_mov_b32 s12, s34
	s_lshl_b32 s16, s16, 8
	s_lshl_b32 s1, s1, 6
	s_add_i32 s1, s1, s16
	v_add_u32_e32 v192, s1, v202
	s_lshl_b32 s13, s12, 5
	s_lshl_b32 s1, s0, 8
	v_add_u32_e32 v224, 0xffffc000, v192
	s_add_i32 s13, s13, s1
	v_lshrrev_b32_e32 v101, 6, v224
	v_lshl_add_u32 v188, v204, 3, s13
	v_ashrrev_i32_e32 v100, 11, v192
	v_add_u32_e32 v101, 8, v101
	v_cmp_gt_i32_e32 vcc, s94, v192
	v_mov_b64_e32 v[102:103], s[56:57]
	v_ashrrev_i32_e32 v189, 31, v188
	v_cndmask_b32_e32 v104, v101, v100, vcc
	v_mov_b64_e32 v[100:101], s[6:7]
	v_mad_i64_i32 v[100:101], s[16:17], v104, s75, v[100:101]
	v_mad_i64_i32 v[102:103], s[16:17], v104, s75, v[102:103]
	v_lshlrev_b64 v[190:191], 2, v[188:189]
	v_lshl_add_u64 v[104:105], v[100:101], 0, v[190:191]
	v_lshl_add_u64 v[194:195], s[72:73], 0, v[190:191]
	v_lshl_add_u64 v[168:169], v[102:103], 0, v[190:191]
	global_load_dwordx4 v[108:111], v[104:105], off offset:16
	global_load_dwordx4 v[116:119], v[104:105], off
	global_load_dwordx4 v[148:151], v[194:195], off offset:16
	global_load_dwordx4 v[164:167], v[194:195], off
	global_load_dwordx4 v[160:163], v[168:169], off offset:16
	global_load_dwordx4 v[172:175], v[168:169], off
	global_load_dwordx4 v[100:103], v[104:105], off offset:528
	s_nop 0
	global_load_dwordx4 v[104:107], v[104:105], off offset:512
	s_nop 0
	global_load_dwordx4 v[144:147], v[194:195], off offset:528
	global_load_dwordx4 v[156:159], v[194:195], off offset:512
	global_load_dwordx4 v[152:155], v[168:169], off offset:528
	s_nop 0
	global_load_dwordx4 v[168:171], v[168:169], off offset:512
	s_movk_i32 s1, 0x3fff
	v_cmp_lt_i32_e32 vcc, s1, v192
	s_and_saveexec_b64 s[16:17], vcc
	s_xor_b64 s[16:17], exec, s[16:17]
	v_lshlrev_b64 v[196:197], 12, v[224:225]
	v_mov_b32_e32 v193, v225
	v_lshl_add_u64 v[198:199], s[20:21], 0, v[196:197]
	v_lshlrev_b64 v[196:197], 12, v[192:193]
	s_andn2_saveexec_b64 s[16:17], s[16:17]
	v_ashrrev_i32_e32 v193, 31, v192
	v_lshlrev_b64 v[196:197], 12, v[192:193]
	v_lshl_add_u64 v[198:199], s[42:43], 0, v[196:197]
	s_or_b64 exec, exec, s[16:17]
	s_sub_u32 s82, s20, 0x4000000
	s_subb_u32 s83, s21, 0
	s_cmp_ge_u32 s16, 0x4000
	s_cselect_b32 s82, s82, s42
	s_cselect_b32 s83, s83, s43
	v_lshl_add_u32 v206, v192, 12, v190
	v_lshlrev_b32_e32 v213, 4, v204
	v_sub_u32_e32 v206, v206, v213
	v_lshlrev_b32_e32 v213, 11, v192
	v_lshlrev_b32_e32 v209, 6, v192
	v_mov_b32_e32 v207, v206
	v_lshl_add_u32 v208, v188, 1, v213
	global_load_dwordx4 v[232:235], v206, s[82:83] offset:64
	global_load_dwordx4 v[240:243], v206, s[82:83] offset:576
	global_load_dwordx4 v[228:231], v206, s[82:83]
	global_load_dwordx4 v[236:239], v206, s[82:83] offset:512
	v_add_u32_e32 v206, 0x10000, v206
	global_load_dwordx4 v[248:251], v206, s[82:83] offset:64
	global_load_dwordx4 v[220:223], v206, s[82:83] offset:576
	global_load_dwordx4 v[244:247], v206, s[82:83]
	global_load_dwordx4 v[216:219], v206, s[82:83] offset:512
	v_add_u32_e32 v206, 0x10000, v206
	s_waitcnt vmcnt(8)
	v_pk_add_f32 v[172:173], v[172:173], 1.0 op_sel_hi:[1,0]
	v_pk_add_f32 v[154:155], v[154:155], 1.0 op_sel_hi:[1,0]
	v_pk_mul_f32 v[164:165], v[164:165], v[172:173]
	v_pk_add_f32 v[172:173], v[160:161], 1.0 op_sel_hi:[1,0]
	v_pk_add_f32 v[160:161], v[162:163], 1.0 op_sel_hi:[1,0]
	v_pk_mul_f32 v[162:163], v[148:149], v[172:173]
	v_pk_mul_f32 v[160:161], v[150:151], v[160:161]
	v_pk_add_f32 v[148:149], v[170:171], 1.0 op_sel_hi:[1,0]
	v_pk_add_f32 v[150:151], v[168:169], 1.0 op_sel_hi:[1,0]
	v_pk_mul_f32 v[146:147], v[146:147], v[154:155]
	v_lshl_add_u64 v[154:155], v[198:199], 0, v[190:191]
	v_pk_mul_f32 v[148:149], v[158:159], v[148:149]
	v_pk_mul_f32 v[150:151], v[156:157], v[150:151]
	v_pk_add_f32 v[174:175], v[174:175], 1.0 op_sel_hi:[1,0]
	v_pk_add_f32 v[152:153], v[152:153], 1.0 op_sel_hi:[1,0]
	v_pk_mul_f32 v[166:167], v[166:167], v[174:175]
	v_pk_mul_f32 v[144:145], v[144:145], v[152:153]
	v_lshlrev_b64 v[152:153], 11, v[192:193]
	v_lshl_add_u64 v[152:153], s[58:59], 0, v[152:153]
	v_lshlrev_b32_e32 v202, 2, v202
	v_lshl_add_u32 v202, v204, 6, v202
	v_xor_b32_e32 v203, 64, v202
	s_lshl_b32 s0, s0, 2
	v_xor_b32_e32 v202, 0x80, v202
	s_ashr_i32 s1, s0, 31
	s_ashr_i32 s13, s12, 31
	s_lshl_b64 s[0:1], s[0:1], 2
	s_add_u32 s16, s37, s0
	s_addc_u32 s17, s38, s1
	s_lshl_b64 s[0:1], s[12:13], 2
	s_add_u32 s90, s16, s0
	v_cmp_eq_u32_e32 vcc, 0, v204
	s_addc_u32 s91, s17, s1
	s_waitcnt vmcnt(4)
; DI u32x4 pack8(const float* v) { u32x4 w; w.x = pk2(v[0], v[1]); w.y = pk2(v[2], v[3]); w.z = pk2(v[4], v[5]); w.w = pk2(v[6], v[7]); return w; }
; #define xor16_32(s) xor16_32_l((s), fr + 16 * fq)
;     DI void operator()(AccRef acc, const Unit& u, int wr, int wc, int fr, int fq) const {
;     ...
;             for (int m = 0; m < 4; ++m) {
;                 const int row = rb + 16 * m;
;                 const float* xi = row < MP ? xin_p + (size_t)row * 1024 : xin_s + (size_t)(row - MP) * 1024;
;                 float s = 0.f;
; #pragma unroll
;                 for (int bj = 0; bj < 2; ++bj) {
;                     const int c = u.pn * 256 + bj * 128 + cl;
;                     float v[8];
; #pragma unroll
;                     for (int n = 0; n < 2; ++n) {
;                         const f32x4 x = *(const f32x4*)(xi + c + 4 * n);
;                         const f32x4 y = x + gt[bj][n] * acc[ai][bj][m][n];
;                         *(f32x4*)(xout + (size_t)row * 1024 + c + 4 * n) = y;
; #pragma unroll
;                         for (int j = 0; j < 4; ++j) { s += y[j] * y[j]; v[4 * n + j] = ap ? y[j] * gs[bj][n][j] : 0.f; }
;                     }
;                     if (ap) *(u32x4*)(ap + (size_t)row * 1024 + c) = pack8(v);
;                 }
;                 s = xor16_32(s);
;                 if (fq == 0) ssq[(size_t)row * 16 + u.pn * 4 + wc] = s;
	v_permlane32_swap_b32_e32 v228, v232
	v_permlane32_swap_b32_e32 v229, v233
	v_permlane32_swap_b32_e32 v230, v234
	v_permlane32_swap_b32_e32 v231, v235
	v_permlane32_swap_b32_e32 v236, v240
	v_permlane32_swap_b32_e32 v237, v241
	v_permlane32_swap_b32_e32 v238, v242
	v_permlane32_swap_b32_e32 v239, v243
	v_permlane16_swap_b32_e32 v228, v232
	v_permlane16_swap_b32_e32 v229, v233
	v_permlane16_swap_b32_e32 v230, v234
	v_permlane16_swap_b32_e32 v231, v235
	v_permlane16_swap_b32_e32 v236, v240
	v_permlane16_swap_b32_e32 v237, v241
	v_permlane16_swap_b32_e32 v238, v242
	v_permlane16_swap_b32_e32 v239, v243
	v_pk_fma_f32 v[140:141], v[140:141], v[116:117], v[228:229]
	v_pk_fma_f32 v[142:143], v[142:143], v[118:119], v[230:231]
	v_mul_f32_e32 v210, v141, v141
	v_fmac_f32_e32 v210, v140, v140
	v_fmac_f32_e32 v210, v142, v142
	v_fmac_f32_e32 v210, v143, v143
	v_pk_mul_f32 v[228:229], v[164:165], v[140:141]
	v_pk_mul_f32 v[230:231], v[166:167], v[142:143]
	v_pk_fma_f32 v[136:137], v[136:137], v[108:109], v[232:233]
	v_pk_fma_f32 v[138:139], v[138:139], v[110:111], v[234:235]
	v_fmac_f32_e32 v210, v136, v136
	v_fmac_f32_e32 v210, v137, v137
	v_fmac_f32_e32 v210, v138, v138
	v_fmac_f32_e32 v210, v139, v139
	v_pk_mul_f32 v[232:233], v[162:163], v[136:137]
	v_pk_mul_f32 v[234:235], v[160:161], v[138:139]
	v_cvt_pk_bf16_f32 v228, v228, v229
	v_cvt_pk_bf16_f32 v229, v230, v231
	v_cvt_pk_bf16_f32 v230, v232, v233
	v_cvt_pk_bf16_f32 v231, v234, v235
	global_store_dwordx4 v208, v[228:231], s[58:59]
	v_pk_fma_f32 v[132:133], v[132:133], v[104:105], v[236:237]
	v_pk_fma_f32 v[134:135], v[134:135], v[106:107], v[238:239]
	v_fmac_f32_e32 v210, v132, v132
	v_fmac_f32_e32 v210, v133, v133
	v_fmac_f32_e32 v210, v134, v134
	v_fmac_f32_e32 v210, v135, v135
	v_pk_mul_f32 v[236:237], v[150:151], v[132:133]
	v_pk_mul_f32 v[238:239], v[148:149], v[134:135]
	v_pk_fma_f32 v[128:129], v[128:129], v[100:101], v[240:241]
	v_pk_fma_f32 v[130:131], v[130:131], v[102:103], v[242:243]
	v_fmac_f32_e32 v210, v128, v128
	v_fmac_f32_e32 v210, v129, v129
	v_fmac_f32_e32 v210, v130, v130
	v_fmac_f32_e32 v210, v131, v131
	v_pk_mul_f32 v[240:241], v[144:145], v[128:129]
	v_pk_mul_f32 v[242:243], v[146:147], v[130:131]
	v_cvt_pk_bf16_f32 v236, v236, v237
	v_cvt_pk_bf16_f32 v237, v238, v239
	v_cvt_pk_bf16_f32 v238, v240, v241
	v_cvt_pk_bf16_f32 v239, v242, v243
	global_store_dwordx4 v208, v[236:239], s[58:59] offset:256
	ds_bpermute_b32 v211, v203, v210
	v_permlane16_swap_b32_e32 v140, v136
	v_permlane16_swap_b32_e32 v141, v137
	v_permlane16_swap_b32_e32 v142, v138
	v_permlane16_swap_b32_e32 v143, v139
	v_permlane16_swap_b32_e32 v132, v128
	v_permlane16_swap_b32_e32 v133, v129
	v_permlane16_swap_b32_e32 v134, v130
	v_permlane16_swap_b32_e32 v135, v131
	v_permlane32_swap_b32_e32 v140, v136
	v_permlane32_swap_b32_e32 v141, v137
	v_permlane32_swap_b32_e32 v142, v138
	v_permlane32_swap_b32_e32 v143, v139
	v_permlane32_swap_b32_e32 v132, v128
	v_permlane32_swap_b32_e32 v133, v129
	v_permlane32_swap_b32_e32 v134, v130
	v_permlane32_swap_b32_e32 v135, v131
	global_store_dwordx4 v207, v[140:143], s[92:93]
	global_store_dwordx4 v207, v[136:139], s[92:93] offset:64
	global_store_dwordx4 v207, v[132:135], s[92:93] offset:512
	global_store_dwordx4 v207, v[128:131], s[92:93] offset:576
	v_add_u32_e32 v207, 0x10000, v207
	global_load_dwordx4 v[232:235], v206, s[82:83] offset:64
	global_load_dwordx4 v[240:243], v206, s[82:83] offset:576
	global_load_dwordx4 v[228:231], v206, s[82:83]
	global_load_dwordx4 v[236:239], v206, s[82:83] offset:512
	s_waitcnt lgkmcnt(0)
	v_add_f32_e32 v211, v210, v211
	ds_bpermute_b32 v212, v202, v211
	v_add_u32_e32 v208, 0x8000, v208
	s_waitcnt lgkmcnt(0)
	v_add_f32_e32 v211, v211, v212
	s_mov_b64 exec, 0xffff
	global_store_dword v209, v211, s[90:91]
	s_mov_b64 exec, -1
	v_add_u32_e32 v209, 0x400, v209
	s_waitcnt vmcnt(11)
	v_permlane32_swap_b32_e32 v244, v248
	v_permlane32_swap_b32_e32 v245, v249
	v_permlane32_swap_b32_e32 v246, v250
	v_permlane32_swap_b32_e32 v247, v251
	v_permlane32_swap_b32_e32 v216, v220
	v_permlane32_swap_b32_e32 v217, v221
	v_permlane32_swap_b32_e32 v218, v222
	v_permlane32_swap_b32_e32 v219, v223
	v_permlane16_swap_b32_e32 v244, v248
	v_permlane16_swap_b32_e32 v245, v249
	v_permlane16_swap_b32_e32 v246, v250
	v_permlane16_swap_b32_e32 v247, v251
	v_permlane16_swap_b32_e32 v216, v220
	v_permlane16_swap_b32_e32 v217, v221
	v_permlane16_swap_b32_e32 v218, v222
	v_permlane16_swap_b32_e32 v219, v223
	v_pk_fma_f32 v[124:125], v[124:125], v[116:117], v[244:245]
	v_pk_fma_f32 v[126:127], v[126:127], v[118:119], v[246:247]
	v_mul_f32_e32 v210, v125, v125
	v_fmac_f32_e32 v210, v124, v124
	v_fmac_f32_e32 v210, v126, v126
	v_fmac_f32_e32 v210, v127, v127
	v_pk_mul_f32 v[244:245], v[164:165], v[124:125]
	v_pk_mul_f32 v[246:247], v[166:167], v[126:127]
	v_pk_fma_f32 v[120:121], v[120:121], v[108:109], v[248:249]
	v_pk_fma_f32 v[122:123], v[122:123], v[110:111], v[250:251]
	v_fmac_f32_e32 v210, v120, v120
	v_fmac_f32_e32 v210, v121, v121
	v_fmac_f32_e32 v210, v122, v122
	v_fmac_f32_e32 v210, v123, v123
	v_pk_mul_f32 v[248:249], v[162:163], v[120:121]
	v_pk_mul_f32 v[250:251], v[160:161], v[122:123]
	v_cvt_pk_bf16_f32 v244, v244, v245
	v_cvt_pk_bf16_f32 v245, v246, v247
	v_cvt_pk_bf16_f32 v246, v248, v249
	v_cvt_pk_bf16_f32 v247, v250, v251
	global_store_dwordx4 v208, v[244:247], s[58:59]
	v_pk_fma_f32 v[112:113], v[112:113], v[104:105], v[216:217]
	v_pk_fma_f32 v[114:115], v[114:115], v[106:107], v[218:219]
	v_fmac_f32_e32 v210, v112, v112
	v_fmac_f32_e32 v210, v113, v113
	v_fmac_f32_e32 v210, v114, v114
	v_fmac_f32_e32 v210, v115, v115
	v_pk_mul_f32 v[216:217], v[150:151], v[112:113]
; DI u32x4 pack8(const float* v) { u32x4 w; w.x = pk2(v[0], v[1]); w.y = pk2(v[2], v[3]); w.z = pk2(v[4], v[5]); w.w = pk2(v[6], v[7]); return w; }
; #define xor16_32(s) xor16_32_l((s), fr + 16 * fq)
;     DI void operator()(AccRef acc, const Unit& u, int wr, int wc, int fr, int fq) const {
;     ...
;             for (int m = 0; m < 4; ++m) {
;                 const int row = rb + 16 * m;
;                 const float* xi = row < MP ? xin_p + (size_t)row * 1024 : xin_s + (size_t)(row - MP) * 1024;
;                 float s = 0.f;
; #pragma unroll
;                 for (int bj = 0; bj < 2; ++bj) {
;                     const int c = u.pn * 256 + bj * 128 + cl;
;                     float v[8];
; #pragma unroll
;                     for (int n = 0; n < 2; ++n) {
;                         const f32x4 x = *(const f32x4*)(xi + c + 4 * n);
;                         const f32x4 y = x + gt[bj][n] * acc[ai][bj][m][n];
;                         *(f32x4*)(xout + (size_t)row * 1024 + c + 4 * n) = y;
; #pragma unroll
;                         for (int j = 0; j < 4; ++j) { s += y[j] * y[j]; v[4 * n + j] = ap ? y[j] * gs[bj][n][j] : 0.f; }
;                     }
;                     if (ap) *(u32x4*)(ap + (size_t)row * 1024 + c) = pack8(v);
;                 }
;                 s = xor16_32(s);
;                 if (fq == 0) ssq[(size_t)row * 16 + u.pn * 4 + wc] = s;
	v_pk_mul_f32 v[218:219], v[148:149], v[114:115]
	v_pk_fma_f32 v[96:97], v[96:97], v[100:101], v[220:221]
	v_pk_fma_f32 v[98:99], v[98:99], v[102:103], v[222:223]
	v_fmac_f32_e32 v210, v96, v96
	v_fmac_f32_e32 v210, v97, v97
	v_fmac_f32_e32 v210, v98, v98
	v_fmac_f32_e32 v210, v99, v99
	v_pk_mul_f32 v[220:221], v[144:145], v[96:97]
	v_pk_mul_f32 v[222:223], v[146:147], v[98:99]
	v_cvt_pk_bf16_f32 v216, v216, v217
	v_cvt_pk_bf16_f32 v217, v218, v219
	v_cvt_pk_bf16_f32 v218, v220, v221
	v_cvt_pk_bf16_f32 v219, v222, v223
	global_store_dwordx4 v208, v[216:219], s[58:59] offset:256
	ds_bpermute_b32 v211, v203, v210
	v_permlane16_swap_b32_e32 v124, v120
	v_permlane16_swap_b32_e32 v125, v121
	v_permlane16_swap_b32_e32 v126, v122
	v_permlane16_swap_b32_e32 v127, v123
	v_permlane16_swap_b32_e32 v112, v96
	v_permlane16_swap_b32_e32 v113, v97
	v_permlane16_swap_b32_e32 v114, v98
	v_permlane16_swap_b32_e32 v115, v99
	v_permlane32_swap_b32_e32 v124, v120
	v_permlane32_swap_b32_e32 v125, v121
	v_permlane32_swap_b32_e32 v126, v122
	v_permlane32_swap_b32_e32 v127, v123
	v_permlane32_swap_b32_e32 v112, v96
	v_permlane32_swap_b32_e32 v113, v97
	v_permlane32_swap_b32_e32 v114, v98
	v_permlane32_swap_b32_e32 v115, v99
	global_store_dwordx4 v207, v[124:127], s[92:93]
	global_store_dwordx4 v207, v[120:123], s[92:93] offset:64
	global_store_dwordx4 v207, v[112:115], s[92:93] offset:512
	global_store_dwordx4 v207, v[96:99], s[92:93] offset:576
	v_add_u32_e32 v207, 0x10000, v207
	v_add_u32_e32 v206, 0x10000, v206
	global_load_dwordx4 v[248:251], v206, s[82:83] offset:64
	global_load_dwordx4 v[220:223], v206, s[82:83] offset:576
	global_load_dwordx4 v[244:247], v206, s[82:83]
	global_load_dwordx4 v[216:219], v206, s[82:83] offset:512
	s_waitcnt lgkmcnt(0)
	v_add_f32_e32 v211, v210, v211
	ds_bpermute_b32 v212, v202, v211
	v_add_u32_e32 v208, 0x8000, v208
	s_waitcnt lgkmcnt(0)
	v_add_f32_e32 v211, v211, v212
	s_mov_b64 exec, 0xffff
	global_store_dword v209, v211, s[90:91]
	s_mov_b64 exec, -1
	v_add_u32_e32 v209, 0x400, v209
	s_waitcnt vmcnt(12)
	v_permlane32_swap_b32_e32 v228, v232
	v_permlane32_swap_b32_e32 v229, v233
	v_permlane32_swap_b32_e32 v230, v234
	v_permlane32_swap_b32_e32 v231, v235
	v_permlane32_swap_b32_e32 v236, v240
	v_permlane32_swap_b32_e32 v237, v241
	v_permlane32_swap_b32_e32 v238, v242
	v_permlane32_swap_b32_e32 v239, v243
	v_permlane16_swap_b32_e32 v228, v232
	v_permlane16_swap_b32_e32 v229, v233
	v_permlane16_swap_b32_e32 v230, v234
	v_permlane16_swap_b32_e32 v231, v235
	v_permlane16_swap_b32_e32 v236, v240
	v_permlane16_swap_b32_e32 v237, v241
	v_permlane16_swap_b32_e32 v238, v242
	v_permlane16_swap_b32_e32 v239, v243
	v_pk_fma_f32 v[92:93], v[92:93], v[116:117], v[228:229]
	v_pk_fma_f32 v[94:95], v[94:95], v[118:119], v[230:231]
	v_mul_f32_e32 v210, v93, v93
	v_fmac_f32_e32 v210, v92, v92
	v_fmac_f32_e32 v210, v94, v94
	v_fmac_f32_e32 v210, v95, v95
	v_pk_mul_f32 v[228:229], v[164:165], v[92:93]
	v_pk_mul_f32 v[230:231], v[166:167], v[94:95]
	v_pk_fma_f32 v[88:89], v[88:89], v[108:109], v[232:233]
	v_pk_fma_f32 v[90:91], v[90:91], v[110:111], v[234:235]
	v_fmac_f32_e32 v210, v88, v88
	v_fmac_f32_e32 v210, v89, v89
	v_fmac_f32_e32 v210, v90, v90
	v_fmac_f32_e32 v210, v91, v91
	v_pk_mul_f32 v[232:233], v[162:163], v[88:89]
	v_pk_mul_f32 v[234:235], v[160:161], v[90:91]
	v_cvt_pk_bf16_f32 v228, v228, v229
	v_cvt_pk_bf16_f32 v229, v230, v231
	v_cvt_pk_bf16_f32 v230, v232, v233
	v_cvt_pk_bf16_f32 v231, v234, v235
	global_store_dwordx4 v208, v[228:231], s[58:59]
	v_pk_fma_f32 v[84:85], v[84:85], v[104:105], v[236:237]
	v_pk_fma_f32 v[86:87], v[86:87], v[106:107], v[238:239]
	v_fmac_f32_e32 v210, v84, v84
	v_fmac_f32_e32 v210, v85, v85
	v_fmac_f32_e32 v210, v86, v86
	v_fmac_f32_e32 v210, v87, v87
	v_pk_mul_f32 v[236:237], v[150:151], v[84:85]
	v_pk_mul_f32 v[238:239], v[148:149], v[86:87]
	v_pk_fma_f32 v[80:81], v[80:81], v[100:101], v[240:241]
	v_pk_fma_f32 v[82:83], v[82:83], v[102:103], v[242:243]
	v_fmac_f32_e32 v210, v80, v80
	v_fmac_f32_e32 v210, v81, v81
	v_fmac_f32_e32 v210, v82, v82
	v_fmac_f32_e32 v210, v83, v83
	v_pk_mul_f32 v[240:241], v[144:145], v[80:81]
	v_pk_mul_f32 v[242:243], v[146:147], v[82:83]
	v_cvt_pk_bf16_f32 v236, v236, v237
	v_cvt_pk_bf16_f32 v237, v238, v239
	v_cvt_pk_bf16_f32 v238, v240, v241
	v_cvt_pk_bf16_f32 v239, v242, v243
	global_store_dwordx4 v208, v[236:239], s[58:59] offset:256
	ds_bpermute_b32 v211, v203, v210
	v_permlane16_swap_b32_e32 v92, v88
	v_permlane16_swap_b32_e32 v93, v89
	v_permlane16_swap_b32_e32 v94, v90
	v_permlane16_swap_b32_e32 v95, v91
	v_permlane16_swap_b32_e32 v84, v80
	v_permlane16_swap_b32_e32 v85, v81
	v_permlane16_swap_b32_e32 v86, v82
	v_permlane16_swap_b32_e32 v87, v83
	v_permlane32_swap_b32_e32 v92, v88
	v_permlane32_swap_b32_e32 v93, v89
	v_permlane32_swap_b32_e32 v94, v90
	v_permlane32_swap_b32_e32 v95, v91
	v_permlane32_swap_b32_e32 v84, v80
	v_permlane32_swap_b32_e32 v85, v81
	v_permlane32_swap_b32_e32 v86, v82
	v_permlane32_swap_b32_e32 v87, v83
	global_store_dwordx4 v207, v[92:95], s[92:93]
	global_store_dwordx4 v207, v[88:91], s[92:93] offset:64
	global_store_dwordx4 v207, v[84:87], s[92:93] offset:512
	global_store_dwordx4 v207, v[80:83], s[92:93] offset:576
	v_add_u32_e32 v207, 0x10000, v207
	v_add_u32_e32 v206, 0x50000, v206
	global_load_dwordx4 v[232:235], v206, s[82:83] offset:64
	global_load_dwordx4 v[240:243], v206, s[82:83] offset:576
	global_load_dwordx4 v[228:231], v206, s[82:83]
	global_load_dwordx4 v[236:239], v206, s[82:83] offset:512
	s_waitcnt lgkmcnt(0)
	v_add_f32_e32 v211, v210, v211
	ds_bpermute_b32 v212, v202, v211
	v_add_u32_e32 v208, 0x8000, v208
	s_waitcnt lgkmcnt(0)
; DI u32x4 pack8(const float* v) { u32x4 w; w.x = pk2(v[0], v[1]); w.y = pk2(v[2], v[3]); w.z = pk2(v[4], v[5]); w.w = pk2(v[6], v[7]); return w; }
; #define xor16_32(s) xor16_32_l((s), fr + 16 * fq)
;     DI void operator()(AccRef acc, const Unit& u, int wr, int wc, int fr, int fq) const {
;     ...
;         for (int ai = 0; ai < 2; ++ai) {
;             const int rb = u.pm * 256 + ai * 128 + wr * 64 + fr;
;             int mb, pos0, kv0; row_info(rb, mb, pos0, kv0);
;             f32x4 gt[2][2], gs[2][2];
; #pragma unroll
;             for (int bj = 0; bj < 2; ++bj)
; #pragma unroll
;                 for (int n = 0; n < 2; ++n) {
;                     const int c = u.pn * 256 + bj * 128 + cl + 4 * n;
;                     gt[bj][n] = *(const f32x4*)(gate + (size_t)mb * 6144 + c);
;                     if (ap) { const f32x4 g = *(const f32x4*)(gn + c), s = *(const f32x4*)(scn + (size_t)mb * 6144 + c); gs[bj][n] = g * (s + 1.f); }
;     ...
;             for (int m = 0; m < 4; ++m) {
;                 const int row = rb + 16 * m;
;                 const float* xi = row < MP ? xin_p + (size_t)row * 1024 : xin_s + (size_t)(row - MP) * 1024;
;                 float s = 0.f;
; #pragma unroll
;                 for (int bj = 0; bj < 2; ++bj) {
;                     const int c = u.pn * 256 + bj * 128 + cl;
;                     float v[8];
; #pragma unroll
;                     for (int n = 0; n < 2; ++n) {
;                         const f32x4 x = *(const f32x4*)(xi + c + 4 * n);
;                         const f32x4 y = x + gt[bj][n] * acc[ai][bj][m][n];
;                         *(f32x4*)(xout + (size_t)row * 1024 + c + 4 * n) = y;
; #pragma unroll
;                         for (int j = 0; j < 4; ++j) { s += y[j] * y[j]; v[4 * n + j] = ap ? y[j] * gs[bj][n][j] : 0.f; }
;                     }
;                     if (ap) *(u32x4*)(ap + (size_t)row * 1024 + c) = pack8(v);
;                 }
;                 s = xor16_32(s);
;                 if (fq == 0) ssq[(size_t)row * 16 + u.pn * 4 + wc] = s;
	v_add_f32_e32 v211, v211, v212
	s_mov_b64 exec, 0xffff
	global_store_dword v209, v211, s[90:91]
	s_mov_b64 exec, -1
	v_add_u32_e32 v209, 0x400, v209
	s_waitcnt vmcnt(12)
	v_permlane32_swap_b32_e32 v244, v248
	v_permlane32_swap_b32_e32 v245, v249
	v_permlane32_swap_b32_e32 v246, v250
	v_permlane32_swap_b32_e32 v247, v251
	v_permlane32_swap_b32_e32 v216, v220
	v_permlane32_swap_b32_e32 v217, v221
	v_permlane32_swap_b32_e32 v218, v222
	v_permlane32_swap_b32_e32 v219, v223
	v_permlane16_swap_b32_e32 v244, v248
	v_permlane16_swap_b32_e32 v245, v249
	v_permlane16_swap_b32_e32 v246, v250
	v_permlane16_swap_b32_e32 v247, v251
	v_permlane16_swap_b32_e32 v216, v220
	v_permlane16_swap_b32_e32 v217, v221
	v_permlane16_swap_b32_e32 v218, v222
	v_permlane16_swap_b32_e32 v219, v223
	v_pk_fma_f32 v[76:77], v[76:77], v[116:117], v[244:245]
	v_pk_fma_f32 v[78:79], v[78:79], v[118:119], v[246:247]
	v_mul_f32_e32 v210, v77, v77
	v_fmac_f32_e32 v210, v76, v76
	v_fmac_f32_e32 v210, v78, v78
	v_fmac_f32_e32 v210, v79, v79
	v_pk_mul_f32 v[244:245], v[164:165], v[76:77]
	v_pk_mul_f32 v[246:247], v[166:167], v[78:79]
	v_pk_fma_f32 v[72:73], v[72:73], v[108:109], v[248:249]
	v_pk_fma_f32 v[74:75], v[74:75], v[110:111], v[250:251]
	v_fmac_f32_e32 v210, v72, v72
	v_fmac_f32_e32 v210, v73, v73
	v_fmac_f32_e32 v210, v74, v74
	v_fmac_f32_e32 v210, v75, v75
	v_pk_mul_f32 v[248:249], v[162:163], v[72:73]
	v_pk_mul_f32 v[250:251], v[160:161], v[74:75]
	v_cvt_pk_bf16_f32 v244, v244, v245
	v_cvt_pk_bf16_f32 v245, v246, v247
	v_cvt_pk_bf16_f32 v246, v248, v249
	v_cvt_pk_bf16_f32 v247, v250, v251
	global_store_dwordx4 v208, v[244:247], s[58:59]
	v_pk_fma_f32 v[68:69], v[68:69], v[104:105], v[216:217]
	v_pk_fma_f32 v[70:71], v[70:71], v[106:107], v[218:219]
	v_fmac_f32_e32 v210, v68, v68
	v_fmac_f32_e32 v210, v69, v69
	v_fmac_f32_e32 v210, v70, v70
	v_fmac_f32_e32 v210, v71, v71
	v_pk_mul_f32 v[216:217], v[150:151], v[68:69]
	v_pk_mul_f32 v[218:219], v[148:149], v[70:71]
	v_pk_fma_f32 v[64:65], v[64:65], v[100:101], v[220:221]
	v_pk_fma_f32 v[66:67], v[66:67], v[102:103], v[222:223]
	v_fmac_f32_e32 v210, v64, v64
	v_fmac_f32_e32 v210, v65, v65
	v_fmac_f32_e32 v210, v66, v66
	v_fmac_f32_e32 v210, v67, v67
	v_pk_mul_f32 v[220:221], v[144:145], v[64:65]
	v_pk_mul_f32 v[222:223], v[146:147], v[66:67]
	v_cvt_pk_bf16_f32 v216, v216, v217
	v_cvt_pk_bf16_f32 v217, v218, v219
	v_cvt_pk_bf16_f32 v218, v220, v221
	v_cvt_pk_bf16_f32 v219, v222, v223
	global_store_dwordx4 v208, v[216:219], s[58:59] offset:256
	ds_bpermute_b32 v211, v203, v210
	v_permlane16_swap_b32_e32 v76, v72
	v_permlane16_swap_b32_e32 v77, v73
	v_permlane16_swap_b32_e32 v78, v74
	v_permlane16_swap_b32_e32 v79, v75
	v_permlane16_swap_b32_e32 v68, v64
	v_permlane16_swap_b32_e32 v69, v65
	v_permlane16_swap_b32_e32 v70, v66
	v_permlane16_swap_b32_e32 v71, v67
	v_permlane32_swap_b32_e32 v76, v72
	v_permlane32_swap_b32_e32 v77, v73
	v_permlane32_swap_b32_e32 v78, v74
	v_permlane32_swap_b32_e32 v79, v75
	v_permlane32_swap_b32_e32 v68, v64
	v_permlane32_swap_b32_e32 v69, v65
	v_permlane32_swap_b32_e32 v70, v66
	v_permlane32_swap_b32_e32 v71, v67
	global_store_dwordx4 v207, v[76:79], s[92:93]
	global_store_dwordx4 v207, v[72:75], s[92:93] offset:64
	global_store_dwordx4 v207, v[68:71], s[92:93] offset:512
	global_store_dwordx4 v207, v[64:67], s[92:93] offset:576
	v_add_u32_e32 v207, 0x50000, v207
	v_add_u32_e32 v206, 0x10000, v206
	global_load_dwordx4 v[248:251], v206, s[82:83] offset:64
	global_load_dwordx4 v[220:223], v206, s[82:83] offset:576
	global_load_dwordx4 v[244:247], v206, s[82:83]
	global_load_dwordx4 v[216:219], v206, s[82:83] offset:512
	s_waitcnt lgkmcnt(0)
	v_add_f32_e32 v211, v210, v211
	ds_bpermute_b32 v212, v202, v211
	v_add_u32_e32 v208, 0x28000, v208
	s_waitcnt lgkmcnt(0)
	v_add_f32_e32 v211, v211, v212
	s_mov_b64 exec, 0xffff
	global_store_dword v209, v211, s[90:91]
	s_mov_b64 exec, -1
	v_add_u32_e32 v209, 0x1400, v209
	v_add_u32_e32 v224, 0xffffc080, v192
	v_add_u32_e32 v112, 0x80, v192
	s_waitcnt lgkmcnt(0)
	v_lshrrev_b32_e32 v65, 6, v224
	v_ashrrev_i32_e32 v64, 11, v112
	v_add_u32_e32 v65, 8, v65
	v_cmp_gt_i32_e64 s[0:1], s94, v112
	v_mov_b64_e32 v[66:67], s[56:57]
	s_nop 0
	v_cndmask_b32_e64 v68, v65, v64, s[0:1]
	v_mov_b64_e32 v[64:65], s[6:7]
	v_mad_i64_i32 v[64:65], s[0:1], v68, s75, v[64:65]
	v_mad_i64_i32 v[66:67], s[0:1], v68, s75, v[66:67]
	v_lshl_add_u64 v[68:69], v[64:65], 0, v[190:191]
	v_lshl_add_u64 v[104:105], v[66:67], 0, v[190:191]
	global_load_dwordx4 v[72:75], v[68:69], off offset:16
	global_load_dwordx4 v[76:79], v[68:69], off
	global_load_dwordx4 v[84:87], v[194:195], off offset:16
	global_load_dwordx4 v[100:103], v[194:195], off
	global_load_dwordx4 v[96:99], v[104:105], off offset:16
	global_load_dwordx4 v[108:111], v[104:105], off
	global_load_dwordx4 v[64:67], v[68:69], off offset:528
	s_nop 0
	global_load_dwordx4 v[68:71], v[68:69], off offset:512
	s_nop 0
	global_load_dwordx4 v[80:83], v[194:195], off offset:528
	global_load_dwordx4 v[92:95], v[194:195], off offset:512
	global_load_dwordx4 v[88:91], v[104:105], off offset:528
	s_nop 0
	global_load_dwordx4 v[104:107], v[104:105], off offset:512
	s_movk_i32 s0, 0x3fff
	v_cmp_lt_i32_e64 s[0:1], s0, v112
	s_and_saveexec_b64 s[12:13], s[0:1]
	s_xor_b64 s[0:1], exec, s[12:13]
	v_lshlrev_b64 v[114:115], 12, v[224:225]
	v_mov_b32_e32 v113, v225
	v_lshl_add_u64 v[116:117], s[20:21], 0, v[114:115]
	v_lshlrev_b64 v[114:115], 12, v[112:113]
	s_andn2_saveexec_b64 s[0:1], s[0:1]
	v_ashrrev_i32_e32 v113, 31, v112
	v_lshlrev_b64 v[114:115], 12, v[112:113]
	v_lshl_add_u64 v[116:117], s[42:43], 0, v[114:115]
	s_or_b64 exec, exec, s[0:1]
	s_waitcnt vmcnt(6)
; DI u32x4 pack8(const float* v) { u32x4 w; w.x = pk2(v[0], v[1]); w.y = pk2(v[2], v[3]); w.z = pk2(v[4], v[5]); w.w = pk2(v[6], v[7]); return w; }
; #define xor16_32(s) xor16_32_l((s), fr + 16 * fq)
;     DI void operator()(AccRef acc, const Unit& u, int wr, int wc, int fr, int fq) const {
;     ...
;                     if (ap) { const f32x4 g = *(const f32x4*)(gn + c), s = *(const f32x4*)(scn + (size_t)mb * 6144 + c); gs[bj][n] = g * (s + 1.f); }
;                 }
; #pragma unroll
;             for (int m = 0; m < 4; ++m) {
;                 const int row = rb + 16 * m;
;                 const float* xi = row < MP ? xin_p + (size_t)row * 1024 : xin_s + (size_t)(row - MP) * 1024;
;                 float s = 0.f;
; #pragma unroll
;                 for (int bj = 0; bj < 2; ++bj) {
;                     const int c = u.pn * 256 + bj * 128 + cl;
;                     float v[8];
; #pragma unroll
;                     for (int n = 0; n < 2; ++n) {
;                         const f32x4 x = *(const f32x4*)(xi + c + 4 * n);
;                         const f32x4 y = x + gt[bj][n] * acc[ai][bj][m][n];
;                         *(f32x4*)(xout + (size_t)row * 1024 + c + 4 * n) = y;
; #pragma unroll
;                         for (int j = 0; j < 4; ++j) { s += y[j] * y[j]; v[4 * n + j] = ap ? y[j] * gs[bj][n][j] : 0.f; }
;                     }
;                     if (ap) *(u32x4*)(ap + (size_t)row * 1024 + c) = pack8(v);
;                 }
;                 s = xor16_32(s);
;                 if (fq == 0) ssq[(size_t)row * 16 + u.pn * 4 + wc] = s;
	v_pk_add_f32 v[108:109], v[108:109], 1.0 op_sel_hi:[1,0]
	s_waitcnt vmcnt(1)
	v_pk_add_f32 v[90:91], v[90:91], 1.0 op_sel_hi:[1,0]
	v_pk_mul_f32 v[100:101], v[100:101], v[108:109]
	v_pk_add_f32 v[108:109], v[96:97], 1.0 op_sel_hi:[1,0]
	v_pk_add_f32 v[96:97], v[98:99], 1.0 op_sel_hi:[1,0]
	v_pk_mul_f32 v[98:99], v[84:85], v[108:109]
	v_pk_mul_f32 v[96:97], v[86:87], v[96:97]
	s_waitcnt vmcnt(0)
	v_pk_add_f32 v[84:85], v[106:107], 1.0 op_sel_hi:[1,0]
	v_pk_add_f32 v[86:87], v[104:105], 1.0 op_sel_hi:[1,0]
	v_pk_mul_f32 v[82:83], v[82:83], v[90:91]
	v_lshl_add_u64 v[90:91], v[116:117], 0, v[190:191]
	v_pk_mul_f32 v[84:85], v[94:95], v[84:85]
	v_pk_mul_f32 v[86:87], v[92:93], v[86:87]
	v_pk_add_f32 v[110:111], v[110:111], 1.0 op_sel_hi:[1,0]
	v_pk_add_f32 v[88:89], v[88:89], 1.0 op_sel_hi:[1,0]
	v_pk_mul_f32 v[102:103], v[102:103], v[110:111]
	v_pk_mul_f32 v[80:81], v[80:81], v[88:89]
	v_lshlrev_b64 v[88:89], 11, v[112:113]
	v_lshl_add_u64 v[88:89], s[58:59], 0, v[88:89]
	v_permlane32_swap_b32_e32 v228, v232
	v_permlane32_swap_b32_e32 v229, v233
	v_permlane32_swap_b32_e32 v230, v234
	v_permlane32_swap_b32_e32 v231, v235
	v_permlane32_swap_b32_e32 v236, v240
	v_permlane32_swap_b32_e32 v237, v241
	v_permlane32_swap_b32_e32 v238, v242
	v_permlane32_swap_b32_e32 v239, v243
	v_permlane16_swap_b32_e32 v228, v232
	v_permlane16_swap_b32_e32 v229, v233
	v_permlane16_swap_b32_e32 v230, v234
	v_permlane16_swap_b32_e32 v231, v235
	v_permlane16_swap_b32_e32 v236, v240
	v_permlane16_swap_b32_e32 v237, v241
	v_permlane16_swap_b32_e32 v238, v242
	v_permlane16_swap_b32_e32 v239, v243
	v_pk_fma_f32 v[60:61], v[60:61], v[76:77], v[228:229]
	v_pk_fma_f32 v[62:63], v[62:63], v[78:79], v[230:231]
	v_mul_f32_e32 v210, v61, v61
	v_fmac_f32_e32 v210, v60, v60
	v_fmac_f32_e32 v210, v62, v62
	v_fmac_f32_e32 v210, v63, v63
	v_pk_mul_f32 v[228:229], v[100:101], v[60:61]
	v_pk_mul_f32 v[230:231], v[102:103], v[62:63]
	v_pk_fma_f32 v[56:57], v[56:57], v[72:73], v[232:233]
	v_pk_fma_f32 v[58:59], v[58:59], v[74:75], v[234:235]
	v_fmac_f32_e32 v210, v56, v56
	v_fmac_f32_e32 v210, v57, v57
	v_fmac_f32_e32 v210, v58, v58
	v_fmac_f32_e32 v210, v59, v59
	v_pk_mul_f32 v[232:233], v[98:99], v[56:57]
	v_pk_mul_f32 v[234:235], v[96:97], v[58:59]
	v_cvt_pk_bf16_f32 v228, v228, v229
	v_cvt_pk_bf16_f32 v229, v230, v231
	v_cvt_pk_bf16_f32 v230, v232, v233
	v_cvt_pk_bf16_f32 v231, v234, v235
	global_store_dwordx4 v208, v[228:231], s[58:59]
	v_pk_fma_f32 v[52:53], v[52:53], v[68:69], v[236:237]
	v_pk_fma_f32 v[54:55], v[54:55], v[70:71], v[238:239]
	v_fmac_f32_e32 v210, v52, v52
	v_fmac_f32_e32 v210, v53, v53
	v_fmac_f32_e32 v210, v54, v54
	v_fmac_f32_e32 v210, v55, v55
	v_pk_mul_f32 v[236:237], v[86:87], v[52:53]
	v_pk_mul_f32 v[238:239], v[84:85], v[54:55]
	v_pk_fma_f32 v[48:49], v[48:49], v[64:65], v[240:241]
	v_pk_fma_f32 v[50:51], v[50:51], v[66:67], v[242:243]
	v_fmac_f32_e32 v210, v48, v48
	v_fmac_f32_e32 v210, v49, v49
	v_fmac_f32_e32 v210, v50, v50
	v_fmac_f32_e32 v210, v51, v51
	v_pk_mul_f32 v[240:241], v[80:81], v[48:49]
	v_pk_mul_f32 v[242:243], v[82:83], v[50:51]
	v_cvt_pk_bf16_f32 v236, v236, v237
	v_cvt_pk_bf16_f32 v237, v238, v239
	v_cvt_pk_bf16_f32 v238, v240, v241
	v_cvt_pk_bf16_f32 v239, v242, v243
	global_store_dwordx4 v208, v[236:239], s[58:59] offset:256
	ds_bpermute_b32 v211, v203, v210
	v_permlane16_swap_b32_e32 v60, v56
	v_permlane16_swap_b32_e32 v61, v57
	v_permlane16_swap_b32_e32 v62, v58
	v_permlane16_swap_b32_e32 v63, v59
	v_permlane16_swap_b32_e32 v52, v48
	v_permlane16_swap_b32_e32 v53, v49
	v_permlane16_swap_b32_e32 v54, v50
	v_permlane16_swap_b32_e32 v55, v51
	v_permlane32_swap_b32_e32 v60, v56
	v_permlane32_swap_b32_e32 v61, v57
	v_permlane32_swap_b32_e32 v62, v58
	v_permlane32_swap_b32_e32 v63, v59
	v_permlane32_swap_b32_e32 v52, v48
	v_permlane32_swap_b32_e32 v53, v49
	v_permlane32_swap_b32_e32 v54, v50
	v_permlane32_swap_b32_e32 v55, v51
	global_store_dwordx4 v207, v[60:63], s[92:93]
	global_store_dwordx4 v207, v[56:59], s[92:93] offset:64
	global_store_dwordx4 v207, v[52:55], s[92:93] offset:512
	global_store_dwordx4 v207, v[48:51], s[92:93] offset:576
	v_add_u32_e32 v207, 0x10000, v207
	v_add_u32_e32 v206, 0x10000, v206
	global_load_dwordx4 v[232:235], v206, s[82:83] offset:64
	global_load_dwordx4 v[240:243], v206, s[82:83] offset:576
	global_load_dwordx4 v[228:231], v206, s[82:83]
	global_load_dwordx4 v[236:239], v206, s[82:83] offset:512
	s_waitcnt lgkmcnt(0)
	v_add_f32_e32 v211, v210, v211
	ds_bpermute_b32 v212, v202, v211
	v_add_u32_e32 v208, 0x8000, v208
	s_waitcnt lgkmcnt(0)
; DI u32x4 pack8(const float* v) { u32x4 w; w.x = pk2(v[0], v[1]); w.y = pk2(v[2], v[3]); w.z = pk2(v[4], v[5]); w.w = pk2(v[6], v[7]); return w; }
; #define xor16_32(s) xor16_32_l((s), fr + 16 * fq)
;     DI void operator()(AccRef acc, const Unit& u, int wr, int wc, int fr, int fq) const {
;     ...
;             for (int m = 0; m < 4; ++m) {
;                 const int row = rb + 16 * m;
;                 const float* xi = row < MP ? xin_p + (size_t)row * 1024 : xin_s + (size_t)(row - MP) * 1024;
;                 float s = 0.f;
; #pragma unroll
;                 for (int bj = 0; bj < 2; ++bj) {
;                     const int c = u.pn * 256 + bj * 128 + cl;
;                     float v[8];
; #pragma unroll
;                     for (int n = 0; n < 2; ++n) {
;                         const f32x4 x = *(const f32x4*)(xi + c + 4 * n);
;                         const f32x4 y = x + gt[bj][n] * acc[ai][bj][m][n];
;                         *(f32x4*)(xout + (size_t)row * 1024 + c + 4 * n) = y;
; #pragma unroll
;                         for (int j = 0; j < 4; ++j) { s += y[j] * y[j]; v[4 * n + j] = ap ? y[j] * gs[bj][n][j] : 0.f; }
;                     }
;                     if (ap) *(u32x4*)(ap + (size_t)row * 1024 + c) = pack8(v);
;                 }
;                 s = xor16_32(s);
;                 if (fq == 0) ssq[(size_t)row * 16 + u.pn * 4 + wc] = s;
	v_add_f32_e32 v211, v211, v212
	s_mov_b64 exec, 0xffff
	global_store_dword v209, v211, s[90:91]
	s_mov_b64 exec, -1
	v_add_u32_e32 v209, 0x400, v209
	v_permlane32_swap_b32_e32 v244, v248
	v_permlane32_swap_b32_e32 v245, v249
	v_permlane32_swap_b32_e32 v246, v250
	v_permlane32_swap_b32_e32 v247, v251
	v_permlane32_swap_b32_e32 v216, v220
	v_permlane32_swap_b32_e32 v217, v221
	v_permlane32_swap_b32_e32 v218, v222
	v_permlane32_swap_b32_e32 v219, v223
	v_permlane16_swap_b32_e32 v244, v248
	v_permlane16_swap_b32_e32 v245, v249
	v_permlane16_swap_b32_e32 v246, v250
	v_permlane16_swap_b32_e32 v247, v251
	v_permlane16_swap_b32_e32 v216, v220
	v_permlane16_swap_b32_e32 v217, v221
	v_permlane16_swap_b32_e32 v218, v222
	v_permlane16_swap_b32_e32 v219, v223
	v_pk_fma_f32 v[44:45], v[44:45], v[76:77], v[244:245]
	v_pk_fma_f32 v[46:47], v[46:47], v[78:79], v[246:247]
	v_mul_f32_e32 v210, v45, v45
	v_fmac_f32_e32 v210, v44, v44
	v_fmac_f32_e32 v210, v46, v46
	v_fmac_f32_e32 v210, v47, v47
	v_pk_mul_f32 v[244:245], v[100:101], v[44:45]
	v_pk_mul_f32 v[246:247], v[102:103], v[46:47]
	v_pk_fma_f32 v[40:41], v[40:41], v[72:73], v[248:249]
	v_pk_fma_f32 v[42:43], v[42:43], v[74:75], v[250:251]
	v_fmac_f32_e32 v210, v40, v40
	v_fmac_f32_e32 v210, v41, v41
	v_fmac_f32_e32 v210, v42, v42
	v_fmac_f32_e32 v210, v43, v43
	v_pk_mul_f32 v[248:249], v[98:99], v[40:41]
	v_pk_mul_f32 v[250:251], v[96:97], v[42:43]
	v_cvt_pk_bf16_f32 v244, v244, v245
	v_cvt_pk_bf16_f32 v245, v246, v247
	v_cvt_pk_bf16_f32 v246, v248, v249
	v_cvt_pk_bf16_f32 v247, v250, v251
	global_store_dwordx4 v208, v[244:247], s[58:59]
	v_pk_fma_f32 v[36:37], v[36:37], v[68:69], v[216:217]
	v_pk_fma_f32 v[38:39], v[38:39], v[70:71], v[218:219]
	v_fmac_f32_e32 v210, v36, v36
	v_fmac_f32_e32 v210, v37, v37
	v_fmac_f32_e32 v210, v38, v38
	v_fmac_f32_e32 v210, v39, v39
	v_pk_mul_f32 v[216:217], v[86:87], v[36:37]
	v_pk_mul_f32 v[218:219], v[84:85], v[38:39]
	v_pk_fma_f32 v[32:33], v[32:33], v[64:65], v[220:221]
	v_pk_fma_f32 v[34:35], v[34:35], v[66:67], v[222:223]
	v_fmac_f32_e32 v210, v32, v32
	v_fmac_f32_e32 v210, v33, v33
	v_fmac_f32_e32 v210, v34, v34
	v_fmac_f32_e32 v210, v35, v35
	v_pk_mul_f32 v[220:221], v[80:81], v[32:33]
	v_pk_mul_f32 v[222:223], v[82:83], v[34:35]
	v_cvt_pk_bf16_f32 v216, v216, v217
	v_cvt_pk_bf16_f32 v217, v218, v219
	v_cvt_pk_bf16_f32 v218, v220, v221
	v_cvt_pk_bf16_f32 v219, v222, v223
	global_store_dwordx4 v208, v[216:219], s[58:59] offset:256
	ds_bpermute_b32 v211, v203, v210
	v_permlane16_swap_b32_e32 v44, v40
	v_permlane16_swap_b32_e32 v45, v41
	v_permlane16_swap_b32_e32 v46, v42
	v_permlane16_swap_b32_e32 v47, v43
	v_permlane16_swap_b32_e32 v36, v32
	v_permlane16_swap_b32_e32 v37, v33
	v_permlane16_swap_b32_e32 v38, v34
	v_permlane16_swap_b32_e32 v39, v35
	v_permlane32_swap_b32_e32 v44, v40
	v_permlane32_swap_b32_e32 v45, v41
	v_permlane32_swap_b32_e32 v46, v42
	v_permlane32_swap_b32_e32 v47, v43
	v_permlane32_swap_b32_e32 v36, v32
	v_permlane32_swap_b32_e32 v37, v33
	v_permlane32_swap_b32_e32 v38, v34
	v_permlane32_swap_b32_e32 v39, v35
	global_store_dwordx4 v207, v[44:47], s[92:93]
	global_store_dwordx4 v207, v[40:43], s[92:93] offset:64
	global_store_dwordx4 v207, v[36:39], s[92:93] offset:512
	global_store_dwordx4 v207, v[32:35], s[92:93] offset:576
	v_add_u32_e32 v207, 0x10000, v207
	v_add_u32_e32 v206, 0x10000, v206
	global_load_dwordx4 v[248:251], v206, s[82:83] offset:64
	global_load_dwordx4 v[220:223], v206, s[82:83] offset:576
	global_load_dwordx4 v[244:247], v206, s[82:83]
	global_load_dwordx4 v[216:219], v206, s[82:83] offset:512
	s_waitcnt lgkmcnt(0)
	v_add_f32_e32 v211, v210, v211
	ds_bpermute_b32 v212, v202, v211
	v_add_u32_e32 v208, 0x8000, v208
	s_waitcnt lgkmcnt(0)
	v_add_f32_e32 v211, v211, v212
	s_mov_b64 exec, 0xffff
	global_store_dword v209, v211, s[90:91]
	s_mov_b64 exec, -1
	v_add_u32_e32 v209, 0x400, v209
	s_waitcnt vmcnt(12)
; DI u32x4 pack8(const float* v) { u32x4 w; w.x = pk2(v[0], v[1]); w.y = pk2(v[2], v[3]); w.z = pk2(v[4], v[5]); w.w = pk2(v[6], v[7]); return w; }
; #define xor16_32(s) xor16_32_l((s), fr + 16 * fq)
; #define otid() otid_w(g_wave)
; #define PG8_BAR __builtin_amdgcn_s_barrier()
; template <class Epi, bool ALIGN_EPI, bool SP2>
; DI void gemm_phase(int g_wave, LAS unsigned char* lds, const Gemm g, const StaticOrder& S, const Epi& E) {
;     ...
;         if constexpr (ALIGN_EPI) { if (wr == 0) PG8_BAR; }
;         { const int t2_ = otid(); int fr_ = t2_ & 15, fq_ = (t2_ >> 4) & 3, wr_ = wr, wc_ = wc; asm volatile("" : "+v"(fr_), "+v"(fq_), "+s"(wr_), "+s"(wc_)); E(acc, cur, wr_, wc_, fr_, fq_); }
;         if (!has_next) break;
; #pragma unroll
;         for (int a = 0; a < 2; ++a)
; #pragma unroll
;             for (int b = 0; b < 2; ++b)
; #pragma unroll
;                 for (int m = 0; m < 4; ++m)
; #pragma unroll
;                     for (int n = 0; n < 2; ++n) acc[a][b][m][n] = (f32x4){0.f, 0.f, 0.f, 0.f};
;         cur = nxt; cA = nA; cB = nB; ++ui;
;         if constexpr (ALIGN_EPI) { if (wr == 1) PG8_BAR; }
;     }
;     DI void operator()(AccRef acc, const Unit& u, int wr, int wc, int fr, int fq) const {
;     ...
;             for (int m = 0; m < 4; ++m) {
;                 const int row = rb + 16 * m;
;                 const float* xi = row < MP ? xin_p + (size_t)row * 1024 : xin_s + (size_t)(row - MP) * 1024;
;                 float s = 0.f;
; #pragma unroll
;                 for (int bj = 0; bj < 2; ++bj) {
;                     const int c = u.pn * 256 + bj * 128 + cl;
;                     float v[8];
; #pragma unroll
;                     for (int n = 0; n < 2; ++n) {
;                         const f32x4 x = *(const f32x4*)(xi + c + 4 * n);
;                         const f32x4 y = x + gt[bj][n] * acc[ai][bj][m][n];
;                         *(f32x4*)(xout + (size_t)row * 1024 + c + 4 * n) = y;
; #pragma unroll
;                         for (int j = 0; j < 4; ++j) { s += y[j] * y[j]; v[4 * n + j] = ap ? y[j] * gs[bj][n][j] : 0.f; }
;                     }
;                     if (ap) *(u32x4*)(ap + (size_t)row * 1024 + c) = pack8(v);
;                 }
;                 s = xor16_32(s);
;                 if (fq == 0) ssq[(size_t)row * 16 + u.pn * 4 + wc] = s;
	v_permlane32_swap_b32_e32 v228, v232
	v_permlane32_swap_b32_e32 v229, v233
	v_permlane32_swap_b32_e32 v230, v234
	v_permlane32_swap_b32_e32 v231, v235
	v_permlane32_swap_b32_e32 v236, v240
	v_permlane32_swap_b32_e32 v237, v241
	v_permlane32_swap_b32_e32 v238, v242
	v_permlane32_swap_b32_e32 v239, v243
	v_permlane16_swap_b32_e32 v228, v232
	v_permlane16_swap_b32_e32 v229, v233
	v_permlane16_swap_b32_e32 v230, v234
	v_permlane16_swap_b32_e32 v231, v235
	v_permlane16_swap_b32_e32 v236, v240
	v_permlane16_swap_b32_e32 v237, v241
	v_permlane16_swap_b32_e32 v238, v242
	v_permlane16_swap_b32_e32 v239, v243
	v_pk_fma_f32 v[28:29], v[28:29], v[76:77], v[228:229]
	v_pk_fma_f32 v[30:31], v[30:31], v[78:79], v[230:231]
	v_mul_f32_e32 v210, v29, v29
	v_fmac_f32_e32 v210, v28, v28
	v_fmac_f32_e32 v210, v30, v30
	v_fmac_f32_e32 v210, v31, v31
	v_pk_mul_f32 v[228:229], v[100:101], v[28:29]
	v_pk_mul_f32 v[230:231], v[102:103], v[30:31]
	v_pk_fma_f32 v[24:25], v[24:25], v[72:73], v[232:233]
	v_pk_fma_f32 v[26:27], v[26:27], v[74:75], v[234:235]
	v_fmac_f32_e32 v210, v24, v24
	v_fmac_f32_e32 v210, v25, v25
	v_fmac_f32_e32 v210, v26, v26
	v_fmac_f32_e32 v210, v27, v27
	v_pk_mul_f32 v[232:233], v[98:99], v[24:25]
	v_pk_mul_f32 v[234:235], v[96:97], v[26:27]
	v_cvt_pk_bf16_f32 v228, v228, v229
	v_cvt_pk_bf16_f32 v229, v230, v231
	v_cvt_pk_bf16_f32 v230, v232, v233
	v_cvt_pk_bf16_f32 v231, v234, v235
	global_store_dwordx4 v208, v[228:231], s[58:59]
	v_pk_fma_f32 v[20:21], v[20:21], v[68:69], v[236:237]
	v_pk_fma_f32 v[22:23], v[22:23], v[70:71], v[238:239]
	v_fmac_f32_e32 v210, v20, v20
	v_fmac_f32_e32 v210, v21, v21
	v_fmac_f32_e32 v210, v22, v22
	v_fmac_f32_e32 v210, v23, v23
	v_pk_mul_f32 v[236:237], v[86:87], v[20:21]
	v_pk_mul_f32 v[238:239], v[84:85], v[22:23]
	v_pk_fma_f32 v[16:17], v[16:17], v[64:65], v[240:241]
	v_pk_fma_f32 v[18:19], v[18:19], v[66:67], v[242:243]
	v_fmac_f32_e32 v210, v16, v16
	v_fmac_f32_e32 v210, v17, v17
	v_fmac_f32_e32 v210, v18, v18
	v_fmac_f32_e32 v210, v19, v19
	v_pk_mul_f32 v[240:241], v[80:81], v[16:17]
	v_pk_mul_f32 v[242:243], v[82:83], v[18:19]
	v_cvt_pk_bf16_f32 v236, v236, v237
	v_cvt_pk_bf16_f32 v237, v238, v239
	v_cvt_pk_bf16_f32 v238, v240, v241
	v_cvt_pk_bf16_f32 v239, v242, v243
	global_store_dwordx4 v208, v[236:239], s[58:59] offset:256
	ds_bpermute_b32 v211, v203, v210
	v_permlane16_swap_b32_e32 v28, v24
	v_permlane16_swap_b32_e32 v29, v25
	v_permlane16_swap_b32_e32 v30, v26
	v_permlane16_swap_b32_e32 v31, v27
	v_permlane16_swap_b32_e32 v20, v16
	v_permlane16_swap_b32_e32 v21, v17
	v_permlane16_swap_b32_e32 v22, v18
	v_permlane16_swap_b32_e32 v23, v19
	v_permlane32_swap_b32_e32 v28, v24
	v_permlane32_swap_b32_e32 v29, v25
	v_permlane32_swap_b32_e32 v30, v26
	v_permlane32_swap_b32_e32 v31, v27
	v_permlane32_swap_b32_e32 v20, v16
	v_permlane32_swap_b32_e32 v21, v17
	v_permlane32_swap_b32_e32 v22, v18
	v_permlane32_swap_b32_e32 v23, v19
	global_store_dwordx4 v207, v[28:31], s[92:93]
	global_store_dwordx4 v207, v[24:27], s[92:93] offset:64
	global_store_dwordx4 v207, v[20:23], s[92:93] offset:512
	global_store_dwordx4 v207, v[16:19], s[92:93] offset:576
	v_add_u32_e32 v207, 0x10000, v207
	s_waitcnt lgkmcnt(0)
	v_add_f32_e32 v211, v210, v211
	ds_bpermute_b32 v212, v202, v211
	v_add_u32_e32 v208, 0x8000, v208
	s_waitcnt lgkmcnt(0)
	v_add_f32_e32 v211, v211, v212
	s_mov_b64 exec, 0xffff
	global_store_dword v209, v211, s[90:91]
	s_mov_b64 exec, -1
	v_add_u32_e32 v209, 0x400, v209
	s_waitcnt vmcnt(8)
	v_permlane32_swap_b32_e32 v244, v248
	v_permlane32_swap_b32_e32 v245, v249
	v_permlane32_swap_b32_e32 v246, v250
	v_permlane32_swap_b32_e32 v247, v251
	v_permlane32_swap_b32_e32 v216, v220
	v_permlane32_swap_b32_e32 v217, v221
	v_permlane32_swap_b32_e32 v218, v222
	v_permlane32_swap_b32_e32 v219, v223
	v_permlane16_swap_b32_e32 v244, v248
	v_permlane16_swap_b32_e32 v245, v249
	v_permlane16_swap_b32_e32 v246, v250
	v_permlane16_swap_b32_e32 v247, v251
	v_permlane16_swap_b32_e32 v216, v220
	v_permlane16_swap_b32_e32 v217, v221
	v_permlane16_swap_b32_e32 v218, v222
	v_permlane16_swap_b32_e32 v219, v223
	v_pk_fma_f32 v[12:13], v[12:13], v[76:77], v[244:245]
	v_pk_fma_f32 v[14:15], v[14:15], v[78:79], v[246:247]
	v_mul_f32_e32 v210, v13, v13
	v_fmac_f32_e32 v210, v12, v12
	v_fmac_f32_e32 v210, v14, v14
	v_fmac_f32_e32 v210, v15, v15
	v_pk_mul_f32 v[244:245], v[100:101], v[12:13]
	v_pk_mul_f32 v[246:247], v[102:103], v[14:15]
	v_pk_fma_f32 v[8:9], v[8:9], v[72:73], v[248:249]
	v_pk_fma_f32 v[10:11], v[10:11], v[74:75], v[250:251]
	v_fmac_f32_e32 v210, v8, v8
	v_fmac_f32_e32 v210, v9, v9
	v_fmac_f32_e32 v210, v10, v10
	v_fmac_f32_e32 v210, v11, v11
	v_pk_mul_f32 v[248:249], v[98:99], v[8:9]
	v_pk_mul_f32 v[250:251], v[96:97], v[10:11]
	v_cvt_pk_bf16_f32 v244, v244, v245
	v_cvt_pk_bf16_f32 v245, v246, v247
	v_cvt_pk_bf16_f32 v246, v248, v249
	v_cvt_pk_bf16_f32 v247, v250, v251
	global_store_dwordx4 v208, v[244:247], s[58:59]
	v_pk_fma_f32 v[4:5], v[4:5], v[68:69], v[216:217]
	v_pk_fma_f32 v[6:7], v[6:7], v[70:71], v[218:219]
	v_fmac_f32_e32 v210, v4, v4
	v_fmac_f32_e32 v210, v5, v5
	v_fmac_f32_e32 v210, v6, v6
	v_fmac_f32_e32 v210, v7, v7
	v_pk_mul_f32 v[216:217], v[86:87], v[4:5]
	v_pk_mul_f32 v[218:219], v[84:85], v[6:7]
	v_pk_fma_f32 v[0:1], v[0:1], v[64:65], v[220:221]
	v_pk_fma_f32 v[2:3], v[2:3], v[66:67], v[222:223]
	v_fmac_f32_e32 v210, v0, v0
	v_fmac_f32_e32 v210, v1, v1
	v_fmac_f32_e32 v210, v2, v2
	v_fmac_f32_e32 v210, v3, v3
	v_pk_mul_f32 v[220:221], v[80:81], v[0:1]
	v_pk_mul_f32 v[222:223], v[82:83], v[2:3]
	v_cvt_pk_bf16_f32 v216, v216, v217
	v_cvt_pk_bf16_f32 v217, v218, v219
	v_cvt_pk_bf16_f32 v218, v220, v221
	v_cvt_pk_bf16_f32 v219, v222, v223
	global_store_dwordx4 v208, v[216:219], s[58:59] offset:256
	ds_bpermute_b32 v211, v203, v210
	v_permlane16_swap_b32_e32 v12, v8
	v_permlane16_swap_b32_e32 v13, v9
	v_permlane16_swap_b32_e32 v14, v10
	v_permlane16_swap_b32_e32 v15, v11
	v_permlane16_swap_b32_e32 v4, v0
	v_permlane16_swap_b32_e32 v5, v1
	v_permlane16_swap_b32_e32 v6, v2
	v_permlane16_swap_b32_e32 v7, v3
	v_permlane32_swap_b32_e32 v12, v8
	v_permlane32_swap_b32_e32 v13, v9
	v_permlane32_swap_b32_e32 v14, v10
	v_permlane32_swap_b32_e32 v15, v11
	v_permlane32_swap_b32_e32 v4, v0
	v_permlane32_swap_b32_e32 v5, v1
	v_permlane32_swap_b32_e32 v6, v2
	v_permlane32_swap_b32_e32 v7, v3
	global_store_dwordx4 v207, v[12:15], s[92:93]
	global_store_dwordx4 v207, v[8:11], s[92:93] offset:64
	global_store_dwordx4 v207, v[4:7], s[92:93] offset:512
	global_store_dwordx4 v207, v[0:3], s[92:93] offset:576
	s_waitcnt lgkmcnt(0)
	v_add_f32_e32 v211, v210, v211
	ds_bpermute_b32 v212, v202, v211
	s_waitcnt lgkmcnt(0)
	v_add_f32_e32 v211, v211, v212
	s_mov_b64 exec, 0xffff
	global_store_dword v209, v211, s[90:91]
	s_mov_b64 exec, -1
	s_andn2_b64 vcc, exec, s[8:9]
	s_mov_b64 s[0:1], -1
	s_cbranch_vccnz .LBB0_1292
	s_andn2_b64 vcc, exec, s[2:3]
	s_cbranch_vccnz .LBB0_1291
	s_barrier
	s_branch .LBB0_1291
